# GU phases: first-half ssq partials of the SwiGLU epilogue prefetched at the start of each tile's K-loop (epilogue no longer starts with an L2 round trip + vmcnt(0))
# speedup vs baseline: 1.0183x; 1.0022x over previous
.LBB0_160:
	s_ashr_i32 s13, s12, 31
	s_lshl_b64 s[14:15], s[12:13], 19
	s_add_u32 s14, s60, s14
	s_addc_u32 s15, s61, s15
	s_and_b64 s[16:17], s[0:1], exec
	s_cselect_b32 s13, s15, s23
	s_cselect_b32 s50, s14, s22
	s_ashr_i32 s11, s10, 31
	s_lshl_b64 s[16:17], s[10:11], 19
	s_add_u32 s16, s68, s16
	s_addc_u32 s17, s69, s17
	s_and_b64 s[26:27], s[0:1], exec
	s_cselect_b32 s11, s17, s25
	s_cselect_b32 s51, s16, s24
	s_add_u32 s22, s22, 0x40080
	s_addc_u32 s23, s23, 0
	s_add_u32 s64, s24, 0x100
	v_mov_b32_e32 v0, 0
	s_addc_u32 s65, s25, 0
	s_mov_b32 s66, -2
	v_mov_b32_e32 v1, v0
	v_mov_b32_e32 v2, v0
	v_mov_b32_e32 v3, v0
	v_mov_b32_e32 v4, v0
	v_mov_b32_e32 v5, v0
	v_mov_b32_e32 v6, v0
	v_mov_b32_e32 v7, v0
	v_mov_b32_e32 v16, v0
	v_mov_b32_e32 v17, v0
	v_mov_b32_e32 v18, v0
	v_mov_b32_e32 v19, v0
	v_mov_b32_e32 v20, v0
	v_mov_b32_e32 v21, v0
	v_mov_b32_e32 v22, v0
	v_mov_b32_e32 v23, v0
	v_mov_b32_e32 v32, v0
	v_mov_b32_e32 v33, v0
	v_mov_b32_e32 v34, v0
	v_mov_b32_e32 v35, v0
	v_mov_b32_e32 v36, v0
	v_mov_b32_e32 v37, v0
	v_mov_b32_e32 v38, v0
	v_mov_b32_e32 v39, v0
	v_mov_b32_e32 v48, v0
	v_mov_b32_e32 v49, v0
	v_mov_b32_e32 v50, v0
	v_mov_b32_e32 v51, v0
	v_mov_b32_e32 v52, v0
	v_mov_b32_e32 v53, v0
	v_mov_b32_e32 v54, v0
	v_mov_b32_e32 v55, v0
	v_mov_b32_e32 v8, v0
	v_mov_b32_e32 v9, v0
	v_mov_b32_e32 v10, v0
	v_mov_b32_e32 v11, v0
	v_mov_b32_e32 v12, v0
	v_mov_b32_e32 v13, v0
	v_mov_b32_e32 v14, v0
	v_mov_b32_e32 v15, v0
	v_mov_b32_e32 v24, v0
	v_mov_b32_e32 v25, v0
	v_mov_b32_e32 v26, v0
	v_mov_b32_e32 v27, v0
	v_mov_b32_e32 v28, v0
	v_mov_b32_e32 v29, v0
	v_mov_b32_e32 v30, v0
	v_mov_b32_e32 v31, v0
	v_mov_b32_e32 v40, v0
	v_mov_b32_e32 v41, v0
	v_mov_b32_e32 v42, v0
	v_mov_b32_e32 v43, v0
	v_mov_b32_e32 v44, v0
	v_mov_b32_e32 v45, v0
	v_mov_b32_e32 v46, v0
	v_mov_b32_e32 v47, v0
	v_mov_b32_e32 v56, v0
	v_mov_b32_e32 v57, v0
	v_mov_b32_e32 v58, v0
	v_mov_b32_e32 v59, v0
	v_mov_b32_e32 v60, v0
	v_mov_b32_e32 v61, v0
	v_mov_b32_e32 v62, v0
	v_mov_b32_e32 v63, v0
	v_mov_b32_e32 v64, v0
	v_mov_b32_e32 v65, v0
	v_mov_b32_e32 v66, v0
	v_mov_b32_e32 v67, v0
	v_mov_b32_e32 v68, v0
	v_mov_b32_e32 v69, v0
	v_mov_b32_e32 v70, v0
	v_mov_b32_e32 v71, v0
	v_mov_b32_e32 v80, v0
	v_mov_b32_e32 v81, v0
	v_mov_b32_e32 v82, v0
	v_mov_b32_e32 v83, v0
	v_mov_b32_e32 v84, v0
	v_mov_b32_e32 v85, v0
	v_mov_b32_e32 v86, v0
	v_mov_b32_e32 v87, v0
	v_mov_b32_e32 v96, v0
	v_mov_b32_e32 v97, v0
	v_mov_b32_e32 v98, v0
	v_mov_b32_e32 v99, v0
	v_mov_b32_e32 v100, v0
	v_mov_b32_e32 v101, v0
	v_mov_b32_e32 v102, v0
	v_mov_b32_e32 v103, v0
	v_mov_b32_e32 v112, v0
	v_mov_b32_e32 v113, v0
	v_mov_b32_e32 v114, v0
	v_mov_b32_e32 v115, v0
	v_mov_b32_e32 v116, v0
	v_mov_b32_e32 v117, v0
	v_mov_b32_e32 v118, v0
	v_mov_b32_e32 v119, v0
	v_mov_b32_e32 v72, v0
	v_mov_b32_e32 v73, v0
	v_mov_b32_e32 v74, v0
	v_mov_b32_e32 v75, v0
	v_mov_b32_e32 v76, v0
	v_mov_b32_e32 v77, v0
	v_mov_b32_e32 v78, v0
	v_mov_b32_e32 v79, v0
	v_mov_b32_e32 v88, v0
	v_mov_b32_e32 v89, v0
	v_mov_b32_e32 v90, v0
	v_mov_b32_e32 v91, v0
	v_mov_b32_e32 v92, v0
	v_mov_b32_e32 v93, v0
	v_mov_b32_e32 v94, v0
	v_mov_b32_e32 v95, v0
	v_mov_b32_e32 v104, v0
	v_mov_b32_e32 v105, v0
	v_mov_b32_e32 v106, v0
	v_mov_b32_e32 v107, v0
	v_mov_b32_e32 v108, v0
	v_mov_b32_e32 v109, v0
	v_mov_b32_e32 v110, v0
	v_mov_b32_e32 v111, v0
	v_mov_b32_e32 v120, v0
	v_mov_b32_e32 v121, v0
	v_mov_b32_e32 v122, v0
	v_mov_b32_e32 v123, v0
	v_mov_b32_e32 v124, v0
	v_mov_b32_e32 v125, v0
	v_mov_b32_e32 v126, v0
	v_mov_b32_e32 v127, v0
	s_lshl_b32 s97, s18, 8
	v_add_u32_e32 v252, s97, v149
	v_mov_b32_e32 v253, 0
	v_lshlrev_b64 v[252:253], 6, v[252:253]
	v_lshl_add_u64 v[254:255], v[136:137], 0, v[252:253]
	global_load_dwordx4 v[236:239], v[254:255], off
	global_load_dwordx4 v[240:243], v[254:255], off offset:1024
	global_load_dwordx4 v[244:247], v[254:255], off offset:2048
	global_load_dwordx4 v[248:251], v[254:255], off offset:3072

.LBB0_164:
	s_lshl_b32 s11, s18, 8
	v_add_u32_e32 v146, s11, v149
	v_or_b32_e32 v162, 16, v146
	v_ashrrev_i32_e32 v147, 31, v146
	v_ashrrev_i32_e32 v163, 31, v162
	v_lshlrev_b64 v[160:161], 6, v[146:147]
	v_lshlrev_b64 v[162:163], 6, v[162:163]
	v_lshl_add_u64 v[160:161], v[136:137], 0, v[160:161]
	v_lshl_add_u64 v[166:167], v[136:137], 0, v[162:163]
	v_mov_b32_e32 v162, v236
	v_mov_b32_e32 v163, v237
	v_mov_b32_e32 v164, v238
	v_mov_b32_e32 v165, v239
	v_mov_b32_e32 v166, v240
	v_mov_b32_e32 v167, v241
	v_mov_b32_e32 v168, v242
	v_mov_b32_e32 v169, v243
	v_or_b32_e32 v160, 32, v146
	v_ashrrev_i32_e32 v161, 31, v160
	v_lshlrev_b64 v[160:161], 6, v[160:161]
	v_lshl_add_u64 v[160:161], v[136:137], 0, v[160:161]
	v_mov_b32_e32 v170, v244
	v_mov_b32_e32 v171, v245
	v_mov_b32_e32 v172, v246
	v_mov_b32_e32 v173, v247
	v_or_b32_e32 v160, 48, v146
	v_ashrrev_i32_e32 v161, 31, v160
	v_lshlrev_b64 v[160:161], 6, v[160:161]
	v_lshl_add_u64 v[160:161], v[136:137], 0, v[160:161]
	v_mov_b32_e32 v174, v248
	v_mov_b32_e32 v175, v249
	v_mov_b32_e32 v176, v250
	v_mov_b32_e32 v177, v251
	v_and_b32_e32 v148, 64, v158
	v_xor_b32_e32 v147, 16, v158
	v_add_u32_e32 v148, 64, v148
	v_xor_b32_e32 v160, 32, v158
	v_cmp_lt_i32_e32 vcc, v147, v148
	v_lshl_or_b32 v178, s49, 7, v154
	v_ashrrev_i32_e32 v179, 31, v178
	v_cndmask_b32_e32 v147, v158, v147, vcc
	v_cmp_lt_i32_e32 vcc, v160, v148
	v_mov_b32_e32 v180, v163
	v_mov_b32_e32 v181, v164
	v_mov_b32_e32 v163, v165
	v_cndmask_b32_e32 v148, v158, v160, vcc
	v_pk_add_f32 v[162:163], v[180:181], v[162:163]
	v_lshlrev_b32_e32 v160, 2, v147
	v_lshlrev_b32_e32 v147, 2, v148
	v_mov_b32_e32 v164, v167
	v_mov_b32_e32 v165, v168
	v_mov_b32_e32 v167, v169
	v_add_f32_e32 v148, v162, v163
	v_mov_b32_e32 v168, v171
	v_mov_b32_e32 v169, v172
	v_mov_b32_e32 v171, v173
	v_pk_add_f32 v[162:163], v[164:165], v[166:167]
	ds_bpermute_b32 v161, v160, v148
	v_mov_b32_e32 v172, v175
	v_mov_b32_e32 v173, v176
	v_mov_b32_e32 v175, v177
	v_pk_add_f32 v[164:165], v[168:169], v[170:171]
	v_add_f32_e32 v162, v162, v163
	v_pk_add_f32 v[166:167], v[172:173], v[174:175]
	v_add_f32_e32 v163, v164, v165
	ds_bpermute_b32 v165, v160, v162
	v_add_f32_e32 v164, v166, v167
	ds_bpermute_b32 v166, v160, v163
	ds_bpermute_b32 v167, v160, v164
	s_waitcnt lgkmcnt(3)
	v_add_f32_e32 v148, v148, v161
	ds_bpermute_b32 v161, v147, v148
	s_waitcnt lgkmcnt(3)
	v_add_f32_e32 v162, v162, v165
	ds_bpermute_b32 v165, v147, v162
	s_waitcnt lgkmcnt(3)
	v_add_f32_e32 v163, v163, v166
	s_waitcnt lgkmcnt(2)
	v_add_f32_e32 v164, v164, v167
	ds_bpermute_b32 v166, v147, v163
	ds_bpermute_b32 v167, v147, v164
	s_waitcnt lgkmcnt(3)
	v_add_f32_e32 v148, v148, v161
	v_fmamk_f32 v148, v148, 0x3a800000, v159
	s_waitcnt lgkmcnt(2)
	v_add_f32_e32 v161, v162, v165
	v_rsq_f32_e32 v162, v148
	s_waitcnt lgkmcnt(1)
	v_add_f32_e32 v163, v163, v166
	s_waitcnt lgkmcnt(0)
	v_add_f32_e32 v164, v164, v167
	v_fmamk_f32 v148, v161, 0x3a800000, v159
	v_fmamk_f32 v161, v163, 0x3a800000, v159
	v_fmamk_f32 v163, v164, 0x3a800000, v159
	v_pk_mul_f32 v[126:127], v[126:127], v[162:163] op_sel_hi:[1,0]
	v_pk_mul_f32 v[124:125], v[124:125], v[162:163] op_sel_hi:[1,0]
	v_pk_mul_f32 v[118:119], v[118:119], v[162:163] op_sel_hi:[1,0]
	v_pk_mul_f32 v[116:117], v[116:117], v[162:163] op_sel_hi:[1,0]
	v_mul_f32_e32 v118, v126, v118
	v_mul_f32_e32 v116, v124, v116
	v_mul_f32_e32 v124, 0xbfb8aa3b, v124
	v_mul_f32_e32 v117, v125, v117
	v_mul_f32_e32 v125, 0xbfb8aa3b, v125
	v_mul_f32_e32 v126, 0xbfb8aa3b, v126
	v_mul_f32_e32 v119, v127, v119
	v_mul_f32_e32 v127, 0xbfb8aa3b, v127
	v_exp_f32_e32 v124, v124
	v_exp_f32_e32 v125, v125
	v_exp_f32_e32 v126, v126
	v_exp_f32_e32 v127, v127
	v_pk_mul_f32 v[120:121], v[120:121], v[162:163] op_sel_hi:[1,0]
	v_pk_mul_f32 v[122:123], v[122:123], v[162:163] op_sel_hi:[1,0]
	v_pk_mul_f32 v[114:115], v[114:115], v[162:163] op_sel_hi:[1,0]
	v_pk_mul_f32 v[112:113], v[112:113], v[162:163] op_sel_hi:[1,0]
	v_mul_f32_e32 v162, 0xbfb8aa3b, v121
	v_add_f32_e32 v124, 1.0, v124
	v_add_f32_e32 v125, 1.0, v125
	v_add_f32_e32 v126, 1.0, v126
	v_exp_f32_e32 v162, v162
	v_add_f32_e32 v127, 1.0, v127
	v_rcp_f32_e32 v124, v124
	v_rcp_f32_e32 v125, v125
	v_rcp_f32_e32 v126, v126
	v_rcp_f32_e32 v127, v127
	v_rsq_f32_e32 v166, v161
	v_mul_f32_e32 v161, 0xbfb8aa3b, v120
	v_exp_f32_e32 v161, v161
	v_add_f32_e32 v162, 1.0, v162
	v_mul_f32_e32 v116, v116, v124
	v_mul_f32_e32 v117, v117, v125
	v_mul_f32_e32 v118, v118, v126
	v_mul_f32_e32 v119, v119, v127
	v_cvt_pk_bf16_f32 v116, v116, v117
	v_cvt_pk_bf16_f32 v117, v118, v119
	v_rcp_f32_e32 v118, v162
	v_add_f32_e32 v161, 1.0, v161
	v_mul_f32_e32 v113, v121, v113
	v_rcp_f32_e32 v161, v161
	v_mul_f32_e32 v113, v113, v118
	v_mul_f32_e32 v118, 0xbfb8aa3b, v122
	v_exp_f32_e32 v119, v118
	v_mul_f32_e32 v118, 0xbfb8aa3b, v123
	v_mul_f32_e32 v112, v120, v112
	v_exp_f32_e32 v120, v118
	v_mul_f32_e32 v112, v112, v161
	v_cvt_pk_bf16_f32 v118, v112, v113
	v_add_f32_e32 v112, 1.0, v119
	v_rcp_f32_e32 v112, v112
	v_add_f32_e32 v113, 1.0, v120
	v_rcp_f32_e32 v113, v113
	v_mul_f32_e32 v114, v122, v114
	v_rsq_f32_e32 v164, v148
	v_mul_f32_e32 v112, v114, v112
	v_mul_f32_e32 v114, v123, v115
	v_mul_f32_e32 v113, v114, v113
	v_cvt_pk_bf16_f32 v119, v112, v113
	v_mov_b64_e32 v[112:113], s[36:37]
	v_mad_i64_i32 v[120:121], s[22:23], v146, s48, v[112:113]
	v_lshlrev_b64 v[114:115], 1, v[178:179]
	v_lshl_add_u64 v[120:121], v[120:121], 0, v[114:115]
	v_pk_mul_f32 v[108:109], v[108:109], v[164:165] op_sel_hi:[1,0]
	global_store_dwordx4 v[120:121], v[116:119], off
	v_pk_mul_f32 v[100:101], v[100:101], v[164:165] op_sel_hi:[1,0]
	v_pk_mul_f32 v[110:111], v[110:111], v[164:165] op_sel_hi:[1,0]
	v_pk_mul_f32 v[116:117], v[98:99], v[164:165] op_sel_hi:[1,0]
	v_mul_f32_e32 v98, 0xbfb8aa3b, v108
	v_exp_f32_e32 v119, v98
	v_mul_f32_e32 v98, 0xbfb8aa3b, v109
	v_exp_f32_e32 v120, v98
	v_pk_mul_f32 v[98:99], v[96:97], v[164:165] op_sel_hi:[1,0]
	v_add_f32_e32 v96, 1.0, v119
	v_rcp_f32_e32 v96, v96
	v_add_f32_e32 v97, 1.0, v120
	v_rcp_f32_e32 v97, v97
	v_mul_f32_e32 v100, v108, v100
	v_mul_f32_e32 v96, v100, v96
	v_mul_f32_e32 v100, v109, v101
	v_mul_f32_e32 v97, v100, v97
	v_mul_f32_e32 v100, 0xbfb8aa3b, v110
	v_exp_f32_e32 v100, v100
	v_mul_f32_e32 v101, 0xbfb8aa3b, v111
	v_exp_f32_e32 v101, v101
	v_cvt_pk_bf16_f32 v96, v96, v97
	v_add_f32_e32 v97, 1.0, v100
	v_rcp_f32_e32 v97, v97
	v_add_f32_e32 v100, 1.0, v101
	v_rcp_f32_e32 v100, v100
	v_pk_mul_f32 v[102:103], v[102:103], v[164:165] op_sel_hi:[1,0]
	v_pk_mul_f32 v[104:105], v[104:105], v[164:165] op_sel_hi:[1,0]
	v_mul_f32_e32 v101, v110, v102
	v_mul_f32_e32 v97, v101, v97
	v_mul_f32_e32 v101, v111, v103
	v_mul_f32_e32 v100, v101, v100
	v_mul_f32_e32 v101, 0xbfb8aa3b, v104
	v_exp_f32_e32 v101, v101
	v_mul_f32_e32 v102, 0xbfb8aa3b, v105
	v_exp_f32_e32 v102, v102
	v_cvt_pk_bf16_f32 v97, v97, v100
	v_add_f32_e32 v100, 1.0, v101
	v_rcp_f32_e32 v100, v100
	v_add_f32_e32 v101, 1.0, v102
	v_rcp_f32_e32 v101, v101
	v_pk_mul_f32 v[106:107], v[106:107], v[164:165] op_sel_hi:[1,0]
	v_mul_f32_e32 v98, v104, v98
	v_mul_f32_e32 v98, v98, v100
	v_mul_f32_e32 v99, v105, v99
	v_mul_f32_e32 v100, 0xbfb8aa3b, v106
	v_mul_f32_e32 v99, v99, v101
	v_exp_f32_e32 v100, v100
	v_mul_f32_e32 v101, 0xbfb8aa3b, v107
	v_exp_f32_e32 v101, v101
	v_cvt_pk_bf16_f32 v98, v98, v99
	v_add_f32_e32 v99, 1.0, v100
	v_rcp_f32_e32 v99, v99
	v_add_f32_e32 v100, 1.0, v101
	v_rcp_f32_e32 v100, v100
	v_mul_f32_e32 v101, v106, v116
	v_mul_f32_e32 v99, v101, v99
	v_mul_f32_e32 v101, v107, v117
	v_add_u32_e32 v118, s11, v151
	v_mul_f32_e32 v100, v101, v100
	v_cvt_pk_bf16_f32 v99, v99, v100
	v_mad_i64_i32 v[100:101], s[22:23], v118, s48, v[112:113]
	v_lshl_add_u64 v[100:101], v[100:101], 0, v[114:115]
	v_pk_mul_f32 v[92:93], v[92:93], v[166:167] op_sel_hi:[1,0]
	global_store_dwordx4 v[100:101], v[96:99], off
	v_pk_mul_f32 v[84:85], v[84:85], v[166:167] op_sel_hi:[1,0]
	v_pk_mul_f32 v[94:95], v[94:95], v[166:167] op_sel_hi:[1,0]
	v_pk_mul_f32 v[96:97], v[82:83], v[166:167] op_sel_hi:[1,0]
	v_mul_f32_e32 v82, 0xbfb8aa3b, v92
	v_exp_f32_e32 v99, v82
	v_mul_f32_e32 v82, 0xbfb8aa3b, v93
	v_exp_f32_e32 v100, v82
	v_pk_mul_f32 v[82:83], v[80:81], v[166:167] op_sel_hi:[1,0]
	v_add_f32_e32 v80, 1.0, v99
	v_rcp_f32_e32 v80, v80
	v_add_f32_e32 v81, 1.0, v100
	v_rcp_f32_e32 v81, v81
	v_mul_f32_e32 v84, v92, v84
	v_mul_f32_e32 v80, v84, v80
	v_mul_f32_e32 v84, v93, v85
	v_mul_f32_e32 v81, v84, v81
	v_mul_f32_e32 v84, 0xbfb8aa3b, v94
	v_exp_f32_e32 v84, v84
	v_mul_f32_e32 v85, 0xbfb8aa3b, v95
	v_exp_f32_e32 v85, v85
	v_cvt_pk_bf16_f32 v80, v80, v81
	v_add_f32_e32 v81, 1.0, v84
	v_rcp_f32_e32 v81, v81
	v_add_f32_e32 v84, 1.0, v85
	v_rcp_f32_e32 v84, v84
	v_pk_mul_f32 v[86:87], v[86:87], v[166:167] op_sel_hi:[1,0]
	v_pk_mul_f32 v[88:89], v[88:89], v[166:167] op_sel_hi:[1,0]
	v_mul_f32_e32 v85, v94, v86
	v_mul_f32_e32 v81, v85, v81
	v_mul_f32_e32 v85, v95, v87
	v_mul_f32_e32 v84, v85, v84
	v_mul_f32_e32 v85, 0xbfb8aa3b, v88
	v_exp_f32_e32 v85, v85
	v_mul_f32_e32 v86, 0xbfb8aa3b, v89
	v_exp_f32_e32 v86, v86
	v_cvt_pk_bf16_f32 v81, v81, v84
	v_add_f32_e32 v84, 1.0, v85
	v_rcp_f32_e32 v84, v84
	v_add_f32_e32 v85, 1.0, v86
	v_rcp_f32_e32 v85, v85
	v_pk_mul_f32 v[90:91], v[90:91], v[166:167] op_sel_hi:[1,0]
	v_mul_f32_e32 v82, v88, v82
	v_mul_f32_e32 v82, v82, v84
	v_mul_f32_e32 v83, v89, v83
	v_mul_f32_e32 v84, 0xbfb8aa3b, v90
	v_mul_f32_e32 v83, v83, v85
	v_exp_f32_e32 v84, v84
	v_mul_f32_e32 v85, 0xbfb8aa3b, v91
	v_exp_f32_e32 v85, v85
	v_cvt_pk_bf16_f32 v82, v82, v83
	v_add_f32_e32 v83, 1.0, v84
	v_rcp_f32_e32 v83, v83
	v_add_f32_e32 v84, 1.0, v85
	v_rcp_f32_e32 v84, v84
	v_rsq_f32_e32 v148, v163
	v_mul_f32_e32 v85, v90, v96
	v_mul_f32_e32 v83, v85, v83
	v_mul_f32_e32 v85, v91, v97
	v_add_u32_e32 v98, s11, v152
	v_mul_f32_e32 v84, v85, v84
	v_cvt_pk_bf16_f32 v83, v83, v84
	v_mad_i64_i32 v[84:85], s[22:23], v98, s48, v[112:113]
	v_lshl_add_u64 v[84:85], v[84:85], 0, v[114:115]
	v_pk_mul_f32 v[76:77], v[76:77], v[148:149] op_sel_hi:[1,0]
	global_store_dwordx4 v[84:85], v[80:83], off
	v_pk_mul_f32 v[68:69], v[68:69], v[148:149] op_sel_hi:[1,0]
	v_pk_mul_f32 v[78:79], v[78:79], v[148:149] op_sel_hi:[1,0]
	v_pk_mul_f32 v[80:81], v[66:67], v[148:149] op_sel_hi:[1,0]
	v_mul_f32_e32 v66, 0xbfb8aa3b, v76
	v_exp_f32_e32 v83, v66
	v_mul_f32_e32 v66, 0xbfb8aa3b, v77
	v_exp_f32_e32 v84, v66
	v_pk_mul_f32 v[66:67], v[64:65], v[148:149] op_sel_hi:[1,0]
	v_add_f32_e32 v64, 1.0, v83
	v_rcp_f32_e32 v64, v64
	v_add_f32_e32 v65, 1.0, v84
	v_rcp_f32_e32 v65, v65
	v_mul_f32_e32 v68, v76, v68
	v_mul_f32_e32 v64, v68, v64
	v_mul_f32_e32 v68, v77, v69
	v_mul_f32_e32 v65, v68, v65
	v_mul_f32_e32 v68, 0xbfb8aa3b, v78
	v_exp_f32_e32 v68, v68
	v_mul_f32_e32 v69, 0xbfb8aa3b, v79
	v_exp_f32_e32 v69, v69
	v_cvt_pk_bf16_f32 v64, v64, v65
	v_add_f32_e32 v65, 1.0, v68
	v_rcp_f32_e32 v65, v65
	v_add_f32_e32 v68, 1.0, v69
	v_rcp_f32_e32 v68, v68
	v_pk_mul_f32 v[70:71], v[70:71], v[148:149] op_sel_hi:[1,0]
	v_pk_mul_f32 v[72:73], v[72:73], v[148:149] op_sel_hi:[1,0]
	v_mul_f32_e32 v69, v78, v70
	v_mul_f32_e32 v65, v69, v65
	v_mul_f32_e32 v69, v79, v71
	v_mul_f32_e32 v68, v69, v68
	v_mul_f32_e32 v69, 0xbfb8aa3b, v72
	v_exp_f32_e32 v69, v69
	v_mul_f32_e32 v70, 0xbfb8aa3b, v73
	v_exp_f32_e32 v70, v70
	v_cvt_pk_bf16_f32 v65, v65, v68
	v_add_f32_e32 v68, 1.0, v69
	v_rcp_f32_e32 v68, v68
	v_add_f32_e32 v69, 1.0, v70
	v_rcp_f32_e32 v69, v69
	v_pk_mul_f32 v[74:75], v[74:75], v[148:149] op_sel_hi:[1,0]
	v_mul_f32_e32 v66, v72, v66
	v_mul_f32_e32 v66, v66, v68
	v_mul_f32_e32 v67, v73, v67
	v_mul_f32_e32 v68, 0xbfb8aa3b, v74
	v_mul_f32_e32 v67, v67, v69
	v_exp_f32_e32 v68, v68
	v_mul_f32_e32 v69, 0xbfb8aa3b, v75
	v_exp_f32_e32 v69, v69
	v_cvt_pk_bf16_f32 v66, v66, v67
	v_add_f32_e32 v67, 1.0, v68
	v_rcp_f32_e32 v67, v67
	v_add_f32_e32 v68, 1.0, v69
	v_rcp_f32_e32 v68, v68
	v_mul_f32_e32 v69, v74, v80
	v_mul_f32_e32 v67, v69, v67
	v_mul_f32_e32 v69, v75, v81
	v_add_u32_e32 v82, s11, v153
	v_mul_f32_e32 v68, v69, v68
	v_cvt_pk_bf16_f32 v67, v67, v68
	v_mad_i64_i32 v[68:69], s[22:23], v82, s48, v[112:113]
	v_add_u32_e32 v88, 0x80, v146
	v_lshl_add_u64 v[68:69], v[68:69], 0, v[114:115]
	v_ashrrev_i32_e32 v89, 31, v88
	global_store_dwordx4 v[68:69], v[64:67], off
	v_add_u32_e32 v70, 0x90, v146
	v_ashrrev_i32_e32 v71, 31, v70
	v_lshlrev_b64 v[64:65], 6, v[88:89]
	v_lshl_add_u64 v[64:65], v[136:137], 0, v[64:65]
	global_load_dwordx4 v[72:75], v[64:65], off
	v_lshlrev_b64 v[64:65], 6, v[70:71]
	v_lshl_add_u64 v[64:65], v[136:137], 0, v[64:65]
	global_load_dwordx4 v[76:79], v[64:65], off
	v_add_u32_e32 v66, 0xa0, v146
	v_ashrrev_i32_e32 v67, 31, v66
	v_lshlrev_b64 v[64:65], 6, v[66:67]
	v_lshl_add_u64 v[64:65], v[136:137], 0, v[64:65]
	global_load_dwordx4 v[80:83], v[64:65], off
	v_add_u32_e32 v64, 0xb0, v146
	v_ashrrev_i32_e32 v65, 31, v64
	v_lshlrev_b64 v[68:69], 6, v[64:65]
	v_lshl_add_u64 v[68:69], v[136:137], 0, v[68:69]
	global_load_dwordx4 v[84:87], v[68:69], off
	s_andn2_b64 vcc, exec, s[0:1]
	s_mov_b64 s[0:1], -1
	s_waitcnt vmcnt(3)
	v_mov_b32_e32 v68, v73
	v_mov_b32_e32 v69, v74
	v_mov_b32_e32 v73, v75
	v_pk_add_f32 v[68:69], v[68:69], v[72:73]
	s_nop 0
	v_add_f32_e32 v65, v68, v69
	ds_bpermute_b32 v67, v160, v65
	s_waitcnt vmcnt(2)
	v_mov_b32_e32 v68, v77
	v_mov_b32_e32 v69, v78
	v_mov_b32_e32 v77, v79
	v_pk_add_f32 v[68:69], v[68:69], v[76:77]
	s_waitcnt lgkmcnt(0)
	v_add_f32_e32 v65, v65, v67
	ds_bpermute_b32 v67, v147, v65
	v_add_f32_e32 v68, v68, v69
	ds_bpermute_b32 v69, v160, v68
	s_waitcnt lgkmcnt(1)
	v_add_f32_e32 v65, v65, v67
	v_fmamk_f32 v65, v65, 0x3a800000, v159
	v_rsq_f32_e32 v72, v65
	s_waitcnt lgkmcnt(0)
	v_add_f32_e32 v65, v68, v69
	s_waitcnt vmcnt(1)
	v_mov_b32_e32 v68, v81
	v_mov_b32_e32 v69, v82
	v_mov_b32_e32 v81, v83
	v_pk_add_f32 v[68:69], v[68:69], v[80:81]
	ds_bpermute_b32 v67, v147, v65
	v_add_f32_e32 v71, v68, v69
	s_waitcnt vmcnt(0)
	v_mov_b32_e32 v68, v85
	v_mov_b32_e32 v69, v86
	v_mov_b32_e32 v85, v87
	ds_bpermute_b32 v73, v160, v71
	v_pk_add_f32 v[68:69], v[68:69], v[84:85]
	s_waitcnt lgkmcnt(1)
	v_add_f32_e32 v65, v65, v67
	v_add_f32_e32 v68, v68, v69
	ds_bpermute_b32 v69, v160, v68
	s_waitcnt lgkmcnt(1)
	v_add_f32_e32 v67, v71, v73
	ds_bpermute_b32 v71, v147, v67
	v_fmamk_f32 v65, v65, 0x3a800000, v159
	v_rsq_f32_e32 v74, v65
	s_waitcnt lgkmcnt(1)
	v_add_f32_e32 v68, v68, v69
	ds_bpermute_b32 v69, v147, v68
	s_waitcnt lgkmcnt(1)
	v_add_f32_e32 v65, v67, v71
	v_fmamk_f32 v65, v65, 0x3a800000, v159
	v_rsq_f32_e32 v76, v65
	v_pk_mul_f32 v[60:61], v[60:61], v[72:73] op_sel_hi:[1,0]
	s_waitcnt lgkmcnt(0)
	v_add_f32_e32 v65, v68, v69
	v_fmamk_f32 v65, v65, 0x3a800000, v159
	v_pk_mul_f32 v[78:79], v[50:51], v[72:73] op_sel_hi:[1,0]
	v_mul_f32_e32 v50, 0xbfb8aa3b, v60
	v_rsq_f32_e32 v68, v65
	v_exp_f32_e32 v65, v50
	v_mul_f32_e32 v50, 0xbfb8aa3b, v61
	v_exp_f32_e32 v67, v50
	v_pk_mul_f32 v[50:51], v[48:49], v[72:73] op_sel_hi:[1,0]
	v_add_f32_e32 v48, 1.0, v65
	v_rcp_f32_e32 v48, v48
	v_add_f32_e32 v49, 1.0, v67
	v_rcp_f32_e32 v49, v49
	v_pk_mul_f32 v[52:53], v[52:53], v[72:73] op_sel_hi:[1,0]
	v_pk_mul_f32 v[62:63], v[62:63], v[72:73] op_sel_hi:[1,0]
	v_mul_f32_e32 v52, v60, v52
	v_mul_f32_e32 v48, v52, v48
	v_mul_f32_e32 v52, v61, v53
	v_mul_f32_e32 v49, v52, v49
	v_mul_f32_e32 v52, 0xbfb8aa3b, v62
	v_exp_f32_e32 v52, v52
	v_mul_f32_e32 v53, 0xbfb8aa3b, v63
	v_exp_f32_e32 v53, v53
	v_cvt_pk_bf16_f32 v48, v48, v49
	v_add_f32_e32 v49, 1.0, v52
	v_rcp_f32_e32 v49, v49
	v_add_f32_e32 v52, 1.0, v53
	v_rcp_f32_e32 v52, v52
	v_pk_mul_f32 v[54:55], v[54:55], v[72:73] op_sel_hi:[1,0]
	v_pk_mul_f32 v[56:57], v[56:57], v[72:73] op_sel_hi:[1,0]
	v_mul_f32_e32 v53, v62, v54
	v_mul_f32_e32 v49, v53, v49
	v_mul_f32_e32 v53, v63, v55
	v_mul_f32_e32 v52, v53, v52
	v_mul_f32_e32 v53, 0xbfb8aa3b, v56
	v_exp_f32_e32 v53, v53
	v_mul_f32_e32 v54, 0xbfb8aa3b, v57
	v_exp_f32_e32 v54, v54
	v_cvt_pk_bf16_f32 v49, v49, v52
	v_add_f32_e32 v52, 1.0, v53
	v_rcp_f32_e32 v52, v52
	v_add_f32_e32 v53, 1.0, v54
	v_rcp_f32_e32 v53, v53
	v_pk_mul_f32 v[58:59], v[58:59], v[72:73] op_sel_hi:[1,0]
	v_mul_f32_e32 v50, v56, v50
	v_mul_f32_e32 v50, v50, v52
	v_mul_f32_e32 v51, v57, v51
	v_mul_f32_e32 v52, 0xbfb8aa3b, v58
	v_mul_f32_e32 v51, v51, v53
	v_exp_f32_e32 v52, v52
	v_mul_f32_e32 v53, 0xbfb8aa3b, v59
	v_exp_f32_e32 v53, v53
	v_cvt_pk_bf16_f32 v50, v50, v51
	v_add_f32_e32 v51, 1.0, v52
	v_rcp_f32_e32 v51, v51
	v_add_f32_e32 v52, 1.0, v53
	v_rcp_f32_e32 v52, v52
	v_mul_f32_e32 v53, v58, v78
	v_mul_f32_e32 v51, v53, v51
	v_mul_f32_e32 v53, v59, v79
	v_mul_f32_e32 v52, v53, v52
	v_cvt_pk_bf16_f32 v51, v51, v52
	v_mad_i64_i32 v[52:53], s[22:23], v88, s48, v[112:113]
	v_lshl_add_u64 v[52:53], v[52:53], 0, v[114:115]
	v_pk_mul_f32 v[44:45], v[44:45], v[74:75] op_sel_hi:[1,0]
	global_store_dwordx4 v[52:53], v[48:51], off
	v_pk_mul_f32 v[36:37], v[36:37], v[74:75] op_sel_hi:[1,0]
	v_pk_mul_f32 v[46:47], v[46:47], v[74:75] op_sel_hi:[1,0]
	v_pk_mul_f32 v[48:49], v[34:35], v[74:75] op_sel_hi:[1,0]
	v_mul_f32_e32 v34, 0xbfb8aa3b, v44
	v_exp_f32_e32 v50, v34
	v_mul_f32_e32 v34, 0xbfb8aa3b, v45
	v_exp_f32_e32 v51, v34
	v_pk_mul_f32 v[34:35], v[32:33], v[74:75] op_sel_hi:[1,0]
	v_add_f32_e32 v32, 1.0, v50
	v_rcp_f32_e32 v32, v32
	v_add_f32_e32 v33, 1.0, v51
	v_rcp_f32_e32 v33, v33
	v_mul_f32_e32 v36, v44, v36
	v_mul_f32_e32 v32, v36, v32
	v_mul_f32_e32 v36, v45, v37
	v_mul_f32_e32 v33, v36, v33
	v_mul_f32_e32 v36, 0xbfb8aa3b, v46
	v_exp_f32_e32 v36, v36
	v_mul_f32_e32 v37, 0xbfb8aa3b, v47
	v_exp_f32_e32 v37, v37
	v_cvt_pk_bf16_f32 v32, v32, v33
	v_add_f32_e32 v33, 1.0, v36
	v_rcp_f32_e32 v33, v33
	v_add_f32_e32 v36, 1.0, v37
	v_rcp_f32_e32 v36, v36
	v_pk_mul_f32 v[38:39], v[38:39], v[74:75] op_sel_hi:[1,0]
	v_pk_mul_f32 v[40:41], v[40:41], v[74:75] op_sel_hi:[1,0]
	v_mul_f32_e32 v37, v46, v38
	v_mul_f32_e32 v33, v37, v33
	v_mul_f32_e32 v37, v47, v39
	v_mul_f32_e32 v36, v37, v36
	v_mul_f32_e32 v37, 0xbfb8aa3b, v40
	v_exp_f32_e32 v37, v37
	v_mul_f32_e32 v38, 0xbfb8aa3b, v41
	v_exp_f32_e32 v38, v38
	v_cvt_pk_bf16_f32 v33, v33, v36
	v_add_f32_e32 v36, 1.0, v37
	v_rcp_f32_e32 v36, v36
	v_add_f32_e32 v37, 1.0, v38
	v_rcp_f32_e32 v37, v37
	v_pk_mul_f32 v[42:43], v[42:43], v[74:75] op_sel_hi:[1,0]
	v_mul_f32_e32 v34, v40, v34
	v_mul_f32_e32 v34, v34, v36
	v_mul_f32_e32 v35, v41, v35
	v_mul_f32_e32 v36, 0xbfb8aa3b, v42
	v_mul_f32_e32 v35, v35, v37
	v_exp_f32_e32 v36, v36
	v_mul_f32_e32 v37, 0xbfb8aa3b, v43
	v_exp_f32_e32 v37, v37
	v_cvt_pk_bf16_f32 v34, v34, v35
	v_add_f32_e32 v35, 1.0, v36
	v_rcp_f32_e32 v35, v35
	v_add_f32_e32 v36, 1.0, v37
	v_rcp_f32_e32 v36, v36
	v_mul_f32_e32 v37, v42, v48
	v_mul_f32_e32 v35, v37, v35
	v_mul_f32_e32 v37, v43, v49
	v_mul_f32_e32 v36, v37, v36
	v_cvt_pk_bf16_f32 v35, v35, v36
	v_mad_i64_i32 v[36:37], s[22:23], v70, s48, v[112:113]
	v_lshl_add_u64 v[36:37], v[36:37], 0, v[114:115]
	v_pk_mul_f32 v[28:29], v[28:29], v[76:77] op_sel_hi:[1,0]
	global_store_dwordx4 v[36:37], v[32:35], off
	v_pk_mul_f32 v[20:21], v[20:21], v[76:77] op_sel_hi:[1,0]
	v_pk_mul_f32 v[30:31], v[30:31], v[76:77] op_sel_hi:[1,0]
	v_pk_mul_f32 v[32:33], v[18:19], v[76:77] op_sel_hi:[1,0]
	v_mul_f32_e32 v18, 0xbfb8aa3b, v28
	v_exp_f32_e32 v34, v18
	v_mul_f32_e32 v18, 0xbfb8aa3b, v29
	v_exp_f32_e32 v35, v18
	v_pk_mul_f32 v[18:19], v[16:17], v[76:77] op_sel_hi:[1,0]
	v_add_f32_e32 v16, 1.0, v34
	v_rcp_f32_e32 v16, v16
	v_add_f32_e32 v17, 1.0, v35
	v_rcp_f32_e32 v17, v17
	v_mul_f32_e32 v20, v28, v20
	v_mul_f32_e32 v16, v20, v16
	v_mul_f32_e32 v20, v29, v21
	v_mul_f32_e32 v17, v20, v17
	v_mul_f32_e32 v20, 0xbfb8aa3b, v30
	v_exp_f32_e32 v20, v20
	v_mul_f32_e32 v21, 0xbfb8aa3b, v31
	v_exp_f32_e32 v21, v21
	v_cvt_pk_bf16_f32 v16, v16, v17
	v_add_f32_e32 v17, 1.0, v20
	v_rcp_f32_e32 v17, v17
	v_add_f32_e32 v20, 1.0, v21
	v_rcp_f32_e32 v20, v20
	v_pk_mul_f32 v[22:23], v[22:23], v[76:77] op_sel_hi:[1,0]
	v_pk_mul_f32 v[24:25], v[24:25], v[76:77] op_sel_hi:[1,0]
	v_mul_f32_e32 v21, v30, v22
	v_mul_f32_e32 v17, v21, v17
	v_mul_f32_e32 v21, v31, v23
	v_mul_f32_e32 v20, v21, v20
	v_mul_f32_e32 v21, 0xbfb8aa3b, v24
	v_exp_f32_e32 v21, v21
	v_mul_f32_e32 v22, 0xbfb8aa3b, v25
	v_exp_f32_e32 v22, v22
	v_cvt_pk_bf16_f32 v17, v17, v20
	v_add_f32_e32 v20, 1.0, v21
	v_rcp_f32_e32 v20, v20
	v_add_f32_e32 v21, 1.0, v22
	v_rcp_f32_e32 v21, v21
	v_pk_mul_f32 v[26:27], v[26:27], v[76:77] op_sel_hi:[1,0]
	v_mul_f32_e32 v18, v24, v18
	v_mul_f32_e32 v18, v18, v20
	v_mul_f32_e32 v19, v25, v19
	v_mul_f32_e32 v20, 0xbfb8aa3b, v26
	v_mul_f32_e32 v19, v19, v21
	v_exp_f32_e32 v20, v20
	v_mul_f32_e32 v21, 0xbfb8aa3b, v27
	v_exp_f32_e32 v21, v21
	v_cvt_pk_bf16_f32 v18, v18, v19
	v_add_f32_e32 v19, 1.0, v20
	v_rcp_f32_e32 v19, v19
	v_add_f32_e32 v20, 1.0, v21
	v_rcp_f32_e32 v20, v20
	v_mul_f32_e32 v21, v26, v32
	v_mul_f32_e32 v19, v21, v19
	v_mul_f32_e32 v21, v27, v33
	v_mul_f32_e32 v20, v21, v20
	v_cvt_pk_bf16_f32 v19, v19, v20
	v_mad_i64_i32 v[20:21], s[22:23], v66, s48, v[112:113]
	v_lshl_add_u64 v[20:21], v[20:21], 0, v[114:115]
	v_pk_mul_f32 v[12:13], v[12:13], v[68:69] op_sel_hi:[1,0]
	global_store_dwordx4 v[20:21], v[16:19], off
	v_pk_mul_f32 v[4:5], v[4:5], v[68:69] op_sel_hi:[1,0]
	v_pk_mul_f32 v[14:15], v[14:15], v[68:69] op_sel_hi:[1,0]
	v_pk_mul_f32 v[16:17], v[2:3], v[68:69] op_sel_hi:[1,0]
	v_mul_f32_e32 v2, 0xbfb8aa3b, v12
	v_exp_f32_e32 v18, v2
	v_mul_f32_e32 v2, 0xbfb8aa3b, v13
	v_exp_f32_e32 v19, v2
	v_pk_mul_f32 v[2:3], v[0:1], v[68:69] op_sel_hi:[1,0]
	v_add_f32_e32 v0, 1.0, v18
	v_rcp_f32_e32 v0, v0
	v_add_f32_e32 v1, 1.0, v19
	v_rcp_f32_e32 v1, v1
	v_mul_f32_e32 v4, v12, v4
	v_mul_f32_e32 v0, v4, v0
	v_mul_f32_e32 v4, v13, v5
	v_mul_f32_e32 v1, v4, v1
	v_mul_f32_e32 v4, 0xbfb8aa3b, v14
	v_exp_f32_e32 v4, v4
	v_mul_f32_e32 v5, 0xbfb8aa3b, v15
	v_exp_f32_e32 v5, v5
	v_cvt_pk_bf16_f32 v0, v0, v1
	v_add_f32_e32 v1, 1.0, v4
	v_rcp_f32_e32 v1, v1
	v_add_f32_e32 v4, 1.0, v5
	v_rcp_f32_e32 v4, v4
	v_pk_mul_f32 v[6:7], v[6:7], v[68:69] op_sel_hi:[1,0]
	v_pk_mul_f32 v[8:9], v[8:9], v[68:69] op_sel_hi:[1,0]
	v_mul_f32_e32 v5, v14, v6
	v_mul_f32_e32 v1, v5, v1
	v_mul_f32_e32 v5, v15, v7
	v_mul_f32_e32 v4, v5, v4
	v_mul_f32_e32 v5, 0xbfb8aa3b, v8
	v_exp_f32_e32 v5, v5
	v_mul_f32_e32 v6, 0xbfb8aa3b, v9
	v_exp_f32_e32 v6, v6
	v_cvt_pk_bf16_f32 v1, v1, v4
	v_add_f32_e32 v4, 1.0, v5
	v_rcp_f32_e32 v4, v4
	v_add_f32_e32 v5, 1.0, v6
	v_rcp_f32_e32 v5, v5
	v_pk_mul_f32 v[10:11], v[10:11], v[68:69] op_sel_hi:[1,0]
	v_mul_f32_e32 v2, v8, v2
	v_mul_f32_e32 v2, v2, v4
	v_mul_f32_e32 v3, v9, v3
	v_mul_f32_e32 v4, 0xbfb8aa3b, v10
	v_mul_f32_e32 v3, v3, v5
	v_exp_f32_e32 v4, v4
	v_mul_f32_e32 v5, 0xbfb8aa3b, v11
	v_exp_f32_e32 v5, v5
	v_cvt_pk_bf16_f32 v2, v2, v3
	v_add_f32_e32 v3, 1.0, v4
	v_rcp_f32_e32 v3, v3
	v_add_f32_e32 v4, 1.0, v5
	v_rcp_f32_e32 v4, v4
	v_mul_f32_e32 v5, v10, v16
	v_mul_f32_e32 v3, v5, v3
	v_mul_f32_e32 v5, v11, v17
	v_mul_f32_e32 v4, v5, v4
	v_cvt_pk_bf16_f32 v3, v3, v4
	v_mad_i64_i32 v[4:5], s[22:23], v64, s48, v[112:113]
	v_lshl_add_u64 v[4:5], v[4:5], 0, v[114:115]
	global_store_dwordx4 v[4:5], v[0:3], off
	s_cbranch_vccnz .LBB0_157
	s_andn2_b64 vcc, exec, s[4:5]
	s_cbranch_vccnz .LBB0_156
	s_barrier
	s_branch .LBB0_156

.LBB0_878:
	s_ashr_i32 s13, s12, 31
	s_lshl_b64 s[14:15], s[12:13], 19
	s_add_u32 s14, s60, s14
	s_addc_u32 s15, s61, s15
	s_and_b64 s[16:17], s[0:1], exec
	s_cselect_b32 s13, s15, s23
	s_cselect_b32 s70, s14, s22
	s_ashr_i32 s11, s10, 31
	s_lshl_b64 s[16:17], s[10:11], 19
	s_add_u32 s16, s28, s16
	s_addc_u32 s17, s29, s17
	s_and_b64 s[26:27], s[0:1], exec
	s_cselect_b32 s11, s17, s25
	s_cselect_b32 s71, s16, s24
	s_add_u32 s22, s22, 0x40080
	s_addc_u32 s23, s23, 0
	s_add_u32 s72, s24, 0x100
	v_mov_b32_e32 v0, 0
	s_addc_u32 s73, s25, 0
	s_mov_b32 s74, -2
	v_mov_b32_e32 v1, v0
	v_mov_b32_e32 v2, v0
	v_mov_b32_e32 v3, v0
	v_mov_b32_e32 v4, v0
	v_mov_b32_e32 v5, v0
	v_mov_b32_e32 v6, v0
	v_mov_b32_e32 v7, v0
	v_mov_b32_e32 v16, v0
	v_mov_b32_e32 v17, v0
	v_mov_b32_e32 v18, v0
	v_mov_b32_e32 v19, v0
	v_mov_b32_e32 v20, v0
	v_mov_b32_e32 v21, v0
	v_mov_b32_e32 v22, v0
	v_mov_b32_e32 v23, v0
	v_mov_b32_e32 v32, v0
	v_mov_b32_e32 v33, v0
	v_mov_b32_e32 v34, v0
	v_mov_b32_e32 v35, v0
	s_waitcnt vmcnt(0)
	v_mov_b32_e32 v36, v0
	v_mov_b32_e32 v37, v0
	v_mov_b32_e32 v38, v0
	v_mov_b32_e32 v39, v0
	v_mov_b32_e32 v48, v0
	v_mov_b32_e32 v49, v0
	v_mov_b32_e32 v50, v0
	v_mov_b32_e32 v51, v0
	v_mov_b32_e32 v52, v0
	v_mov_b32_e32 v53, v0
	v_mov_b32_e32 v54, v0
	v_mov_b32_e32 v55, v0
	v_mov_b32_e32 v8, v0
	v_mov_b32_e32 v9, v0
	v_mov_b32_e32 v10, v0
	v_mov_b32_e32 v11, v0
	v_mov_b32_e32 v12, v0
	v_mov_b32_e32 v13, v0
	v_mov_b32_e32 v14, v0
	v_mov_b32_e32 v15, v0
	v_mov_b32_e32 v24, v0
	v_mov_b32_e32 v25, v0
	v_mov_b32_e32 v26, v0
	v_mov_b32_e32 v27, v0
	v_mov_b32_e32 v28, v0
	v_mov_b32_e32 v29, v0
	v_mov_b32_e32 v30, v0
	v_mov_b32_e32 v31, v0
	v_mov_b32_e32 v40, v0
	v_mov_b32_e32 v41, v0
	v_mov_b32_e32 v42, v0
	v_mov_b32_e32 v43, v0
	v_mov_b32_e32 v44, v0
	v_mov_b32_e32 v45, v0
	v_mov_b32_e32 v46, v0
	v_mov_b32_e32 v47, v0
	v_mov_b32_e32 v56, v0
	v_mov_b32_e32 v57, v0
	v_mov_b32_e32 v58, v0
	v_mov_b32_e32 v59, v0
	v_mov_b32_e32 v60, v0
	v_mov_b32_e32 v61, v0
	v_mov_b32_e32 v62, v0
	v_mov_b32_e32 v63, v0
	v_mov_b32_e32 v64, v0
	v_mov_b32_e32 v65, v0
	v_mov_b32_e32 v66, v0
	v_mov_b32_e32 v67, v0
	v_mov_b32_e32 v68, v0
	v_mov_b32_e32 v69, v0
	v_mov_b32_e32 v70, v0
	v_mov_b32_e32 v71, v0
	v_mov_b32_e32 v80, v0
	v_mov_b32_e32 v81, v0
	v_mov_b32_e32 v82, v0
	v_mov_b32_e32 v83, v0
	v_mov_b32_e32 v84, v0
	v_mov_b32_e32 v85, v0
	v_mov_b32_e32 v86, v0
	v_mov_b32_e32 v87, v0
	v_mov_b32_e32 v96, v0
	v_mov_b32_e32 v97, v0
	v_mov_b32_e32 v98, v0
	v_mov_b32_e32 v99, v0
	v_mov_b32_e32 v100, v0
	v_mov_b32_e32 v101, v0
	v_mov_b32_e32 v102, v0
	v_mov_b32_e32 v103, v0
	v_mov_b32_e32 v112, v0
	v_mov_b32_e32 v113, v0
	v_mov_b32_e32 v114, v0
	v_mov_b32_e32 v115, v0
	v_mov_b32_e32 v116, v0
	v_mov_b32_e32 v117, v0
	v_mov_b32_e32 v118, v0
	v_mov_b32_e32 v119, v0
	v_mov_b32_e32 v72, v0
	v_mov_b32_e32 v73, v0
	v_mov_b32_e32 v74, v0
	v_mov_b32_e32 v75, v0
	v_mov_b32_e32 v76, v0
	v_mov_b32_e32 v77, v0
	v_mov_b32_e32 v78, v0
	v_mov_b32_e32 v79, v0
	v_mov_b32_e32 v88, v0
	v_mov_b32_e32 v89, v0
	v_mov_b32_e32 v90, v0
	v_mov_b32_e32 v91, v0
	v_mov_b32_e32 v92, v0
	v_mov_b32_e32 v93, v0
	v_mov_b32_e32 v94, v0
	v_mov_b32_e32 v95, v0
	v_mov_b32_e32 v104, v0
	v_mov_b32_e32 v105, v0
	v_mov_b32_e32 v106, v0
	v_mov_b32_e32 v107, v0
	v_mov_b32_e32 v108, v0
	v_mov_b32_e32 v109, v0
	v_mov_b32_e32 v110, v0
	v_mov_b32_e32 v111, v0
	v_mov_b32_e32 v120, v0
	v_mov_b32_e32 v121, v0
	v_mov_b32_e32 v122, v0
	v_mov_b32_e32 v123, v0
	v_mov_b32_e32 v124, v0
	v_mov_b32_e32 v125, v0
	v_mov_b32_e32 v126, v0
	v_mov_b32_e32 v127, v0
	s_lshl_b32 s97, s18, 8
	v_add_u32_e32 v252, s97, v149
	v_mov_b32_e32 v253, 0
	v_lshlrev_b64 v[252:253], 6, v[252:253]
	v_lshl_add_u64 v[254:255], v[136:137], 0, v[252:253]
	global_load_dwordx4 v[236:239], v[254:255], off
	global_load_dwordx4 v[240:243], v[254:255], off offset:1024
	global_load_dwordx4 v[244:247], v[254:255], off offset:2048
	global_load_dwordx4 v[248:251], v[254:255], off offset:3072

.LBB0_882:
	s_lshl_b32 s11, s18, 8
	v_add_u32_e32 v146, s11, v149
	v_or_b32_e32 v162, 16, v146
	v_ashrrev_i32_e32 v147, 31, v146
	v_ashrrev_i32_e32 v163, 31, v162
	v_lshlrev_b64 v[160:161], 6, v[146:147]
	v_lshlrev_b64 v[162:163], 6, v[162:163]
	v_lshl_add_u64 v[160:161], v[136:137], 0, v[160:161]
	v_lshl_add_u64 v[166:167], v[136:137], 0, v[162:163]
	v_mov_b32_e32 v162, v236
	v_mov_b32_e32 v163, v237
	v_mov_b32_e32 v164, v238
	v_mov_b32_e32 v165, v239
	v_mov_b32_e32 v166, v240
	v_mov_b32_e32 v167, v241
	v_mov_b32_e32 v168, v242
	v_mov_b32_e32 v169, v243
	v_or_b32_e32 v160, 32, v146
	v_ashrrev_i32_e32 v161, 31, v160
	v_lshlrev_b64 v[160:161], 6, v[160:161]
	v_lshl_add_u64 v[160:161], v[136:137], 0, v[160:161]
	v_mov_b32_e32 v170, v244
	v_mov_b32_e32 v171, v245
	v_mov_b32_e32 v172, v246
	v_mov_b32_e32 v173, v247
	v_or_b32_e32 v160, 48, v146
	v_ashrrev_i32_e32 v161, 31, v160
	v_lshlrev_b64 v[160:161], 6, v[160:161]
	v_lshl_add_u64 v[160:161], v[136:137], 0, v[160:161]
	v_mov_b32_e32 v174, v248
	v_mov_b32_e32 v175, v249
	v_mov_b32_e32 v176, v250
	v_mov_b32_e32 v177, v251
	v_and_b32_e32 v148, 64, v158
	v_xor_b32_e32 v147, 16, v158
	v_add_u32_e32 v148, 64, v148
	v_xor_b32_e32 v160, 32, v158
	v_cmp_lt_i32_e32 vcc, v147, v148
	v_lshl_or_b32 v178, s69, 7, v154
	v_ashrrev_i32_e32 v179, 31, v178
	v_cndmask_b32_e32 v147, v158, v147, vcc
	v_cmp_lt_i32_e32 vcc, v160, v148
	v_mov_b32_e32 v180, v163
	v_mov_b32_e32 v181, v164
	v_mov_b32_e32 v163, v165
	v_cndmask_b32_e32 v148, v158, v160, vcc
	v_pk_add_f32 v[162:163], v[180:181], v[162:163]
	v_lshlrev_b32_e32 v160, 2, v147
	v_lshlrev_b32_e32 v147, 2, v148
	v_mov_b32_e32 v164, v167
	v_mov_b32_e32 v165, v168
	v_mov_b32_e32 v167, v169
	v_add_f32_e32 v148, v162, v163
	v_mov_b32_e32 v168, v171
	v_mov_b32_e32 v169, v172
	v_mov_b32_e32 v171, v173
	v_pk_add_f32 v[162:163], v[164:165], v[166:167]
	ds_bpermute_b32 v161, v160, v148
	v_mov_b32_e32 v172, v175
	v_mov_b32_e32 v173, v176
	v_mov_b32_e32 v175, v177
	v_pk_add_f32 v[164:165], v[168:169], v[170:171]
	v_add_f32_e32 v162, v162, v163
	v_pk_add_f32 v[166:167], v[172:173], v[174:175]
	v_add_f32_e32 v163, v164, v165
	ds_bpermute_b32 v165, v160, v162
	v_add_f32_e32 v164, v166, v167
	ds_bpermute_b32 v166, v160, v163
	ds_bpermute_b32 v167, v160, v164
	s_waitcnt lgkmcnt(3)
	v_add_f32_e32 v148, v148, v161
	ds_bpermute_b32 v161, v147, v148
	s_waitcnt lgkmcnt(3)
	v_add_f32_e32 v162, v162, v165
	ds_bpermute_b32 v165, v147, v162
	s_waitcnt lgkmcnt(3)
	v_add_f32_e32 v163, v163, v166
	s_waitcnt lgkmcnt(2)
	v_add_f32_e32 v164, v164, v167
	ds_bpermute_b32 v166, v147, v163
	ds_bpermute_b32 v167, v147, v164
	s_waitcnt lgkmcnt(3)
	v_add_f32_e32 v148, v148, v161
	v_fmamk_f32 v148, v148, 0x3a800000, v159
	s_waitcnt lgkmcnt(2)
	v_add_f32_e32 v161, v162, v165
	v_rsq_f32_e32 v162, v148
	s_waitcnt lgkmcnt(1)
	v_add_f32_e32 v163, v163, v166
	s_waitcnt lgkmcnt(0)
	v_add_f32_e32 v164, v164, v167
	v_fmamk_f32 v148, v161, 0x3a800000, v159
	v_fmamk_f32 v161, v163, 0x3a800000, v159
	v_fmamk_f32 v163, v164, 0x3a800000, v159
	v_pk_mul_f32 v[126:127], v[126:127], v[162:163] op_sel_hi:[1,0]
	v_pk_mul_f32 v[124:125], v[124:125], v[162:163] op_sel_hi:[1,0]
	v_pk_mul_f32 v[118:119], v[118:119], v[162:163] op_sel_hi:[1,0]
	v_pk_mul_f32 v[116:117], v[116:117], v[162:163] op_sel_hi:[1,0]
	v_mul_f32_e32 v118, v126, v118
	v_mul_f32_e32 v116, v124, v116
	v_mul_f32_e32 v124, 0xbfb8aa3b, v124
	v_mul_f32_e32 v117, v125, v117
	v_mul_f32_e32 v125, 0xbfb8aa3b, v125
	v_mul_f32_e32 v126, 0xbfb8aa3b, v126
	v_mul_f32_e32 v119, v127, v119
	v_mul_f32_e32 v127, 0xbfb8aa3b, v127
	v_exp_f32_e32 v124, v124
	v_exp_f32_e32 v125, v125
	v_exp_f32_e32 v126, v126
	v_exp_f32_e32 v127, v127
	v_pk_mul_f32 v[120:121], v[120:121], v[162:163] op_sel_hi:[1,0]
	v_pk_mul_f32 v[122:123], v[122:123], v[162:163] op_sel_hi:[1,0]
	v_pk_mul_f32 v[114:115], v[114:115], v[162:163] op_sel_hi:[1,0]
	v_pk_mul_f32 v[112:113], v[112:113], v[162:163] op_sel_hi:[1,0]
	v_mul_f32_e32 v162, 0xbfb8aa3b, v121
	v_add_f32_e32 v124, 1.0, v124
	v_add_f32_e32 v125, 1.0, v125
	v_add_f32_e32 v126, 1.0, v126
	v_exp_f32_e32 v162, v162
	v_add_f32_e32 v127, 1.0, v127
	v_rcp_f32_e32 v124, v124
	v_rcp_f32_e32 v125, v125
	v_rcp_f32_e32 v126, v126
	v_rcp_f32_e32 v127, v127
	v_rsq_f32_e32 v166, v161
	v_mul_f32_e32 v161, 0xbfb8aa3b, v120
	v_exp_f32_e32 v161, v161
	v_add_f32_e32 v162, 1.0, v162
	v_mul_f32_e32 v116, v116, v124
	v_mul_f32_e32 v117, v117, v125
	v_mul_f32_e32 v118, v118, v126
	v_mul_f32_e32 v119, v119, v127
	v_cvt_pk_bf16_f32 v116, v116, v117
	v_cvt_pk_bf16_f32 v117, v118, v119
	v_rcp_f32_e32 v118, v162
	v_add_f32_e32 v161, 1.0, v161
	v_mul_f32_e32 v113, v121, v113
	v_rcp_f32_e32 v161, v161
	v_mul_f32_e32 v113, v113, v118
	v_mul_f32_e32 v118, 0xbfb8aa3b, v122
	v_exp_f32_e32 v119, v118
	v_mul_f32_e32 v118, 0xbfb8aa3b, v123
	v_mul_f32_e32 v112, v120, v112
	v_exp_f32_e32 v120, v118
	v_mul_f32_e32 v112, v112, v161
	v_cvt_pk_bf16_f32 v118, v112, v113
	v_add_f32_e32 v112, 1.0, v119
	v_rcp_f32_e32 v112, v112
	v_add_f32_e32 v113, 1.0, v120
	v_rcp_f32_e32 v113, v113
	v_mul_f32_e32 v114, v122, v114
	v_rsq_f32_e32 v164, v148
	v_mul_f32_e32 v112, v114, v112
	v_mul_f32_e32 v114, v123, v115
	v_mul_f32_e32 v113, v114, v113
	v_cvt_pk_bf16_f32 v119, v112, v113
	v_mov_b64_e32 v[112:113], s[36:37]
	v_mad_i64_i32 v[120:121], s[22:23], v146, s68, v[112:113]
	v_lshlrev_b64 v[114:115], 1, v[178:179]
	v_lshl_add_u64 v[120:121], v[120:121], 0, v[114:115]
	v_pk_mul_f32 v[108:109], v[108:109], v[164:165] op_sel_hi:[1,0]
	global_store_dwordx4 v[120:121], v[116:119], off
	v_pk_mul_f32 v[100:101], v[100:101], v[164:165] op_sel_hi:[1,0]
	v_pk_mul_f32 v[110:111], v[110:111], v[164:165] op_sel_hi:[1,0]
	v_pk_mul_f32 v[116:117], v[98:99], v[164:165] op_sel_hi:[1,0]
	v_mul_f32_e32 v98, 0xbfb8aa3b, v108
	v_exp_f32_e32 v119, v98
	v_mul_f32_e32 v98, 0xbfb8aa3b, v109
	v_exp_f32_e32 v120, v98
	v_pk_mul_f32 v[98:99], v[96:97], v[164:165] op_sel_hi:[1,0]
	v_add_f32_e32 v96, 1.0, v119
	v_rcp_f32_e32 v96, v96
	v_add_f32_e32 v97, 1.0, v120
	v_rcp_f32_e32 v97, v97
	v_mul_f32_e32 v100, v108, v100
	v_mul_f32_e32 v96, v100, v96
	v_mul_f32_e32 v100, v109, v101
	v_mul_f32_e32 v97, v100, v97
	v_mul_f32_e32 v100, 0xbfb8aa3b, v110
	v_exp_f32_e32 v100, v100
	v_mul_f32_e32 v101, 0xbfb8aa3b, v111
	v_exp_f32_e32 v101, v101
	v_cvt_pk_bf16_f32 v96, v96, v97
	v_add_f32_e32 v97, 1.0, v100
	v_rcp_f32_e32 v97, v97
	v_add_f32_e32 v100, 1.0, v101
	v_rcp_f32_e32 v100, v100
	v_pk_mul_f32 v[102:103], v[102:103], v[164:165] op_sel_hi:[1,0]
	v_pk_mul_f32 v[104:105], v[104:105], v[164:165] op_sel_hi:[1,0]
	v_mul_f32_e32 v101, v110, v102
	v_mul_f32_e32 v97, v101, v97
	v_mul_f32_e32 v101, v111, v103
	v_mul_f32_e32 v100, v101, v100
	v_mul_f32_e32 v101, 0xbfb8aa3b, v104
	v_exp_f32_e32 v101, v101
	v_mul_f32_e32 v102, 0xbfb8aa3b, v105
	v_exp_f32_e32 v102, v102
	v_cvt_pk_bf16_f32 v97, v97, v100
	v_add_f32_e32 v100, 1.0, v101
	v_rcp_f32_e32 v100, v100
	v_add_f32_e32 v101, 1.0, v102
	v_rcp_f32_e32 v101, v101
	v_pk_mul_f32 v[106:107], v[106:107], v[164:165] op_sel_hi:[1,0]
	v_mul_f32_e32 v98, v104, v98
	v_mul_f32_e32 v98, v98, v100
	v_mul_f32_e32 v99, v105, v99
	v_mul_f32_e32 v100, 0xbfb8aa3b, v106
	v_mul_f32_e32 v99, v99, v101
	v_exp_f32_e32 v100, v100
	v_mul_f32_e32 v101, 0xbfb8aa3b, v107
	v_exp_f32_e32 v101, v101
	v_cvt_pk_bf16_f32 v98, v98, v99
	v_add_f32_e32 v99, 1.0, v100
	v_rcp_f32_e32 v99, v99
	v_add_f32_e32 v100, 1.0, v101
	v_rcp_f32_e32 v100, v100
	v_mul_f32_e32 v101, v106, v116
	v_mul_f32_e32 v99, v101, v99
	v_mul_f32_e32 v101, v107, v117
	v_add_u32_e32 v118, s11, v151
	v_mul_f32_e32 v100, v101, v100
	v_cvt_pk_bf16_f32 v99, v99, v100
	v_mad_i64_i32 v[100:101], s[22:23], v118, s68, v[112:113]
	v_lshl_add_u64 v[100:101], v[100:101], 0, v[114:115]
	v_pk_mul_f32 v[92:93], v[92:93], v[166:167] op_sel_hi:[1,0]
	global_store_dwordx4 v[100:101], v[96:99], off
	v_pk_mul_f32 v[84:85], v[84:85], v[166:167] op_sel_hi:[1,0]
	v_pk_mul_f32 v[94:95], v[94:95], v[166:167] op_sel_hi:[1,0]
	v_pk_mul_f32 v[96:97], v[82:83], v[166:167] op_sel_hi:[1,0]
	v_mul_f32_e32 v82, 0xbfb8aa3b, v92
	v_exp_f32_e32 v99, v82
	v_mul_f32_e32 v82, 0xbfb8aa3b, v93
	v_exp_f32_e32 v100, v82
	v_pk_mul_f32 v[82:83], v[80:81], v[166:167] op_sel_hi:[1,0]
	v_add_f32_e32 v80, 1.0, v99
	v_rcp_f32_e32 v80, v80
	v_add_f32_e32 v81, 1.0, v100
	v_rcp_f32_e32 v81, v81
	v_mul_f32_e32 v84, v92, v84
	v_mul_f32_e32 v80, v84, v80
	v_mul_f32_e32 v84, v93, v85
	v_mul_f32_e32 v81, v84, v81
	v_mul_f32_e32 v84, 0xbfb8aa3b, v94
	v_exp_f32_e32 v84, v84
	v_mul_f32_e32 v85, 0xbfb8aa3b, v95
	v_exp_f32_e32 v85, v85
	v_cvt_pk_bf16_f32 v80, v80, v81
	v_add_f32_e32 v81, 1.0, v84
	v_rcp_f32_e32 v81, v81
	v_add_f32_e32 v84, 1.0, v85
	v_rcp_f32_e32 v84, v84
	v_pk_mul_f32 v[86:87], v[86:87], v[166:167] op_sel_hi:[1,0]
	v_pk_mul_f32 v[88:89], v[88:89], v[166:167] op_sel_hi:[1,0]
	v_mul_f32_e32 v85, v94, v86
	v_mul_f32_e32 v81, v85, v81
	v_mul_f32_e32 v85, v95, v87
	v_mul_f32_e32 v84, v85, v84
	v_mul_f32_e32 v85, 0xbfb8aa3b, v88
	v_exp_f32_e32 v85, v85
	v_mul_f32_e32 v86, 0xbfb8aa3b, v89
	v_exp_f32_e32 v86, v86
	v_cvt_pk_bf16_f32 v81, v81, v84
	v_add_f32_e32 v84, 1.0, v85
	v_rcp_f32_e32 v84, v84
	v_add_f32_e32 v85, 1.0, v86
	v_rcp_f32_e32 v85, v85
	v_pk_mul_f32 v[90:91], v[90:91], v[166:167] op_sel_hi:[1,0]
	v_mul_f32_e32 v82, v88, v82
	v_mul_f32_e32 v82, v82, v84
	v_mul_f32_e32 v83, v89, v83
	v_mul_f32_e32 v84, 0xbfb8aa3b, v90
	v_mul_f32_e32 v83, v83, v85
	v_exp_f32_e32 v84, v84
	v_mul_f32_e32 v85, 0xbfb8aa3b, v91
	v_exp_f32_e32 v85, v85
	v_cvt_pk_bf16_f32 v82, v82, v83
	v_add_f32_e32 v83, 1.0, v84
	v_rcp_f32_e32 v83, v83
	v_add_f32_e32 v84, 1.0, v85
	v_rcp_f32_e32 v84, v84
	v_rsq_f32_e32 v148, v163
	v_mul_f32_e32 v85, v90, v96
	v_mul_f32_e32 v83, v85, v83
	v_mul_f32_e32 v85, v91, v97
	v_add_u32_e32 v98, s11, v152
	v_mul_f32_e32 v84, v85, v84
	v_cvt_pk_bf16_f32 v83, v83, v84
	v_mad_i64_i32 v[84:85], s[22:23], v98, s68, v[112:113]
	v_lshl_add_u64 v[84:85], v[84:85], 0, v[114:115]
	v_pk_mul_f32 v[76:77], v[76:77], v[148:149] op_sel_hi:[1,0]
	global_store_dwordx4 v[84:85], v[80:83], off
	v_pk_mul_f32 v[68:69], v[68:69], v[148:149] op_sel_hi:[1,0]
	v_pk_mul_f32 v[78:79], v[78:79], v[148:149] op_sel_hi:[1,0]
	v_pk_mul_f32 v[80:81], v[66:67], v[148:149] op_sel_hi:[1,0]
	v_mul_f32_e32 v66, 0xbfb8aa3b, v76
	v_exp_f32_e32 v83, v66
	v_mul_f32_e32 v66, 0xbfb8aa3b, v77
	v_exp_f32_e32 v84, v66
	v_pk_mul_f32 v[66:67], v[64:65], v[148:149] op_sel_hi:[1,0]
	v_add_f32_e32 v64, 1.0, v83
	v_rcp_f32_e32 v64, v64
	v_add_f32_e32 v65, 1.0, v84
	v_rcp_f32_e32 v65, v65
	v_mul_f32_e32 v68, v76, v68
	v_mul_f32_e32 v64, v68, v64
	v_mul_f32_e32 v68, v77, v69
	v_mul_f32_e32 v65, v68, v65
	v_mul_f32_e32 v68, 0xbfb8aa3b, v78
	v_exp_f32_e32 v68, v68
	v_mul_f32_e32 v69, 0xbfb8aa3b, v79
	v_exp_f32_e32 v69, v69
	v_cvt_pk_bf16_f32 v64, v64, v65
	v_add_f32_e32 v65, 1.0, v68
	v_rcp_f32_e32 v65, v65
	v_add_f32_e32 v68, 1.0, v69
	v_rcp_f32_e32 v68, v68
	v_pk_mul_f32 v[70:71], v[70:71], v[148:149] op_sel_hi:[1,0]
	v_pk_mul_f32 v[72:73], v[72:73], v[148:149] op_sel_hi:[1,0]
	v_mul_f32_e32 v69, v78, v70
	v_mul_f32_e32 v65, v69, v65
	v_mul_f32_e32 v69, v79, v71
	v_mul_f32_e32 v68, v69, v68
	v_mul_f32_e32 v69, 0xbfb8aa3b, v72
	v_exp_f32_e32 v69, v69
	v_mul_f32_e32 v70, 0xbfb8aa3b, v73
	v_exp_f32_e32 v70, v70
	v_cvt_pk_bf16_f32 v65, v65, v68
	v_add_f32_e32 v68, 1.0, v69
	v_rcp_f32_e32 v68, v68
	v_add_f32_e32 v69, 1.0, v70
	v_rcp_f32_e32 v69, v69
	v_pk_mul_f32 v[74:75], v[74:75], v[148:149] op_sel_hi:[1,0]
	v_mul_f32_e32 v66, v72, v66
	v_mul_f32_e32 v66, v66, v68
	v_mul_f32_e32 v67, v73, v67
	v_mul_f32_e32 v68, 0xbfb8aa3b, v74
	v_mul_f32_e32 v67, v67, v69
	v_exp_f32_e32 v68, v68
	v_mul_f32_e32 v69, 0xbfb8aa3b, v75
	v_exp_f32_e32 v69, v69
	v_cvt_pk_bf16_f32 v66, v66, v67
	v_add_f32_e32 v67, 1.0, v68
	v_rcp_f32_e32 v67, v67
	v_add_f32_e32 v68, 1.0, v69
	v_rcp_f32_e32 v68, v68
	v_mul_f32_e32 v69, v74, v80
	v_mul_f32_e32 v67, v69, v67
	v_mul_f32_e32 v69, v75, v81
	v_add_u32_e32 v82, s11, v153
	v_mul_f32_e32 v68, v69, v68
	v_cvt_pk_bf16_f32 v67, v67, v68
	v_mad_i64_i32 v[68:69], s[22:23], v82, s68, v[112:113]
	v_add_u32_e32 v88, 0x80, v146
	v_lshl_add_u64 v[68:69], v[68:69], 0, v[114:115]
	v_ashrrev_i32_e32 v89, 31, v88
	global_store_dwordx4 v[68:69], v[64:67], off
	v_add_u32_e32 v70, 0x90, v146
	v_ashrrev_i32_e32 v71, 31, v70
	v_lshlrev_b64 v[64:65], 6, v[88:89]
	v_lshl_add_u64 v[64:65], v[136:137], 0, v[64:65]
	global_load_dwordx4 v[72:75], v[64:65], off
	v_lshlrev_b64 v[64:65], 6, v[70:71]
	v_lshl_add_u64 v[64:65], v[136:137], 0, v[64:65]
	global_load_dwordx4 v[76:79], v[64:65], off
	v_add_u32_e32 v66, 0xa0, v146
	v_ashrrev_i32_e32 v67, 31, v66
	v_lshlrev_b64 v[64:65], 6, v[66:67]
	v_lshl_add_u64 v[64:65], v[136:137], 0, v[64:65]
	global_load_dwordx4 v[80:83], v[64:65], off
	v_add_u32_e32 v64, 0xb0, v146
	v_ashrrev_i32_e32 v65, 31, v64
	v_lshlrev_b64 v[68:69], 6, v[64:65]
	v_lshl_add_u64 v[68:69], v[136:137], 0, v[68:69]
	global_load_dwordx4 v[84:87], v[68:69], off
	s_andn2_b64 vcc, exec, s[0:1]
	s_mov_b64 s[0:1], -1
	s_waitcnt vmcnt(3)
	v_mov_b32_e32 v68, v73
	v_mov_b32_e32 v69, v74
	v_mov_b32_e32 v73, v75
	v_pk_add_f32 v[68:69], v[68:69], v[72:73]
	s_nop 0
	v_add_f32_e32 v65, v68, v69
	ds_bpermute_b32 v67, v160, v65
	s_waitcnt vmcnt(2)
	v_mov_b32_e32 v68, v77
	v_mov_b32_e32 v69, v78
	v_mov_b32_e32 v77, v79
	v_pk_add_f32 v[68:69], v[68:69], v[76:77]
	s_waitcnt lgkmcnt(0)
	v_add_f32_e32 v65, v65, v67
	ds_bpermute_b32 v67, v147, v65
	v_add_f32_e32 v68, v68, v69
	ds_bpermute_b32 v69, v160, v68
	s_waitcnt lgkmcnt(1)
	v_add_f32_e32 v65, v65, v67
	v_fmamk_f32 v65, v65, 0x3a800000, v159
	v_rsq_f32_e32 v72, v65
	s_waitcnt lgkmcnt(0)
	v_add_f32_e32 v65, v68, v69
	s_waitcnt vmcnt(1)
	v_mov_b32_e32 v68, v81
	v_mov_b32_e32 v69, v82
	v_mov_b32_e32 v81, v83
	v_pk_add_f32 v[68:69], v[68:69], v[80:81]
	ds_bpermute_b32 v67, v147, v65
	v_add_f32_e32 v71, v68, v69
	s_waitcnt vmcnt(0)
	v_mov_b32_e32 v68, v85
	v_mov_b32_e32 v69, v86
	v_mov_b32_e32 v85, v87
	ds_bpermute_b32 v73, v160, v71
	v_pk_add_f32 v[68:69], v[68:69], v[84:85]
	s_waitcnt lgkmcnt(1)
	v_add_f32_e32 v65, v65, v67
	v_add_f32_e32 v68, v68, v69
	ds_bpermute_b32 v69, v160, v68
	s_waitcnt lgkmcnt(1)
	v_add_f32_e32 v67, v71, v73
	ds_bpermute_b32 v71, v147, v67
	v_fmamk_f32 v65, v65, 0x3a800000, v159
	v_rsq_f32_e32 v74, v65
	s_waitcnt lgkmcnt(1)
	v_add_f32_e32 v68, v68, v69
	ds_bpermute_b32 v69, v147, v68
	s_waitcnt lgkmcnt(1)
	v_add_f32_e32 v65, v67, v71
	v_fmamk_f32 v65, v65, 0x3a800000, v159
	v_rsq_f32_e32 v76, v65
	v_pk_mul_f32 v[60:61], v[60:61], v[72:73] op_sel_hi:[1,0]
	s_waitcnt lgkmcnt(0)
	v_add_f32_e32 v65, v68, v69
	v_fmamk_f32 v65, v65, 0x3a800000, v159
	v_pk_mul_f32 v[78:79], v[50:51], v[72:73] op_sel_hi:[1,0]
	v_mul_f32_e32 v50, 0xbfb8aa3b, v60
	v_rsq_f32_e32 v68, v65
	v_exp_f32_e32 v65, v50
	v_mul_f32_e32 v50, 0xbfb8aa3b, v61
	v_exp_f32_e32 v67, v50
	v_pk_mul_f32 v[50:51], v[48:49], v[72:73] op_sel_hi:[1,0]
	v_add_f32_e32 v48, 1.0, v65
	v_rcp_f32_e32 v48, v48
	v_add_f32_e32 v49, 1.0, v67
	v_rcp_f32_e32 v49, v49
	v_pk_mul_f32 v[52:53], v[52:53], v[72:73] op_sel_hi:[1,0]
	v_pk_mul_f32 v[62:63], v[62:63], v[72:73] op_sel_hi:[1,0]
	v_mul_f32_e32 v52, v60, v52
	v_mul_f32_e32 v48, v52, v48
	v_mul_f32_e32 v52, v61, v53
	v_mul_f32_e32 v49, v52, v49
	v_mul_f32_e32 v52, 0xbfb8aa3b, v62
	v_exp_f32_e32 v52, v52
	v_mul_f32_e32 v53, 0xbfb8aa3b, v63
	v_exp_f32_e32 v53, v53
	v_cvt_pk_bf16_f32 v48, v48, v49
	v_add_f32_e32 v49, 1.0, v52
	v_rcp_f32_e32 v49, v49
	v_add_f32_e32 v52, 1.0, v53
	v_rcp_f32_e32 v52, v52
	v_pk_mul_f32 v[54:55], v[54:55], v[72:73] op_sel_hi:[1,0]
	v_pk_mul_f32 v[56:57], v[56:57], v[72:73] op_sel_hi:[1,0]
	v_mul_f32_e32 v53, v62, v54
	v_mul_f32_e32 v49, v53, v49
	v_mul_f32_e32 v53, v63, v55
	v_mul_f32_e32 v52, v53, v52
	v_mul_f32_e32 v53, 0xbfb8aa3b, v56
	v_exp_f32_e32 v53, v53
	v_mul_f32_e32 v54, 0xbfb8aa3b, v57
	v_exp_f32_e32 v54, v54
	v_cvt_pk_bf16_f32 v49, v49, v52
	v_add_f32_e32 v52, 1.0, v53
	v_rcp_f32_e32 v52, v52
	v_add_f32_e32 v53, 1.0, v54
	v_rcp_f32_e32 v53, v53
	v_pk_mul_f32 v[58:59], v[58:59], v[72:73] op_sel_hi:[1,0]
	v_mul_f32_e32 v50, v56, v50
	v_mul_f32_e32 v50, v50, v52
	v_mul_f32_e32 v51, v57, v51
	v_mul_f32_e32 v52, 0xbfb8aa3b, v58
	v_mul_f32_e32 v51, v51, v53
	v_exp_f32_e32 v52, v52
	v_mul_f32_e32 v53, 0xbfb8aa3b, v59
	v_exp_f32_e32 v53, v53
	v_cvt_pk_bf16_f32 v50, v50, v51
	v_add_f32_e32 v51, 1.0, v52
	v_rcp_f32_e32 v51, v51
	v_add_f32_e32 v52, 1.0, v53
	v_rcp_f32_e32 v52, v52
	v_mul_f32_e32 v53, v58, v78
	v_mul_f32_e32 v51, v53, v51
	v_mul_f32_e32 v53, v59, v79
	v_mul_f32_e32 v52, v53, v52
	v_cvt_pk_bf16_f32 v51, v51, v52
	v_mad_i64_i32 v[52:53], s[22:23], v88, s68, v[112:113]
	v_lshl_add_u64 v[52:53], v[52:53], 0, v[114:115]
	v_pk_mul_f32 v[44:45], v[44:45], v[74:75] op_sel_hi:[1,0]
	global_store_dwordx4 v[52:53], v[48:51], off
	v_pk_mul_f32 v[36:37], v[36:37], v[74:75] op_sel_hi:[1,0]
	v_pk_mul_f32 v[46:47], v[46:47], v[74:75] op_sel_hi:[1,0]
	v_pk_mul_f32 v[48:49], v[34:35], v[74:75] op_sel_hi:[1,0]
	v_mul_f32_e32 v34, 0xbfb8aa3b, v44
	v_exp_f32_e32 v50, v34
	v_mul_f32_e32 v34, 0xbfb8aa3b, v45
	v_exp_f32_e32 v51, v34
	v_pk_mul_f32 v[34:35], v[32:33], v[74:75] op_sel_hi:[1,0]
	v_add_f32_e32 v32, 1.0, v50
	v_rcp_f32_e32 v32, v32
	v_add_f32_e32 v33, 1.0, v51
	v_rcp_f32_e32 v33, v33
	v_mul_f32_e32 v36, v44, v36
	v_mul_f32_e32 v32, v36, v32
	v_mul_f32_e32 v36, v45, v37
	v_mul_f32_e32 v33, v36, v33
	v_mul_f32_e32 v36, 0xbfb8aa3b, v46
	v_exp_f32_e32 v36, v36
	v_mul_f32_e32 v37, 0xbfb8aa3b, v47
	v_exp_f32_e32 v37, v37
	v_cvt_pk_bf16_f32 v32, v32, v33
	v_add_f32_e32 v33, 1.0, v36
	v_rcp_f32_e32 v33, v33
	v_add_f32_e32 v36, 1.0, v37
	v_rcp_f32_e32 v36, v36
	v_pk_mul_f32 v[38:39], v[38:39], v[74:75] op_sel_hi:[1,0]
	v_pk_mul_f32 v[40:41], v[40:41], v[74:75] op_sel_hi:[1,0]
	v_mul_f32_e32 v37, v46, v38
	v_mul_f32_e32 v33, v37, v33
	v_mul_f32_e32 v37, v47, v39
	v_mul_f32_e32 v36, v37, v36
	v_mul_f32_e32 v37, 0xbfb8aa3b, v40
	v_exp_f32_e32 v37, v37
	v_mul_f32_e32 v38, 0xbfb8aa3b, v41
	v_exp_f32_e32 v38, v38
	v_cvt_pk_bf16_f32 v33, v33, v36
	v_add_f32_e32 v36, 1.0, v37
	v_rcp_f32_e32 v36, v36
	v_add_f32_e32 v37, 1.0, v38
	v_rcp_f32_e32 v37, v37
	v_pk_mul_f32 v[42:43], v[42:43], v[74:75] op_sel_hi:[1,0]
	v_mul_f32_e32 v34, v40, v34
	v_mul_f32_e32 v34, v34, v36
	v_mul_f32_e32 v35, v41, v35
	v_mul_f32_e32 v36, 0xbfb8aa3b, v42
	v_mul_f32_e32 v35, v35, v37
	v_exp_f32_e32 v36, v36
	v_mul_f32_e32 v37, 0xbfb8aa3b, v43
	v_exp_f32_e32 v37, v37
	v_cvt_pk_bf16_f32 v34, v34, v35
	v_add_f32_e32 v35, 1.0, v36
	v_rcp_f32_e32 v35, v35
	v_add_f32_e32 v36, 1.0, v37
	v_rcp_f32_e32 v36, v36
	v_mul_f32_e32 v37, v42, v48
	v_mul_f32_e32 v35, v37, v35
	v_mul_f32_e32 v37, v43, v49
	v_mul_f32_e32 v36, v37, v36
	v_cvt_pk_bf16_f32 v35, v35, v36
	v_mad_i64_i32 v[36:37], s[22:23], v70, s68, v[112:113]
	v_lshl_add_u64 v[36:37], v[36:37], 0, v[114:115]
	v_pk_mul_f32 v[28:29], v[28:29], v[76:77] op_sel_hi:[1,0]
	global_store_dwordx4 v[36:37], v[32:35], off
	v_pk_mul_f32 v[20:21], v[20:21], v[76:77] op_sel_hi:[1,0]
	v_pk_mul_f32 v[30:31], v[30:31], v[76:77] op_sel_hi:[1,0]
	v_pk_mul_f32 v[32:33], v[18:19], v[76:77] op_sel_hi:[1,0]
	v_mul_f32_e32 v18, 0xbfb8aa3b, v28
	v_exp_f32_e32 v34, v18
	v_mul_f32_e32 v18, 0xbfb8aa3b, v29
	v_exp_f32_e32 v35, v18
	v_pk_mul_f32 v[18:19], v[16:17], v[76:77] op_sel_hi:[1,0]
	v_add_f32_e32 v16, 1.0, v34
	v_rcp_f32_e32 v16, v16
	v_add_f32_e32 v17, 1.0, v35
	v_rcp_f32_e32 v17, v17
	v_mul_f32_e32 v20, v28, v20
	v_mul_f32_e32 v16, v20, v16
	v_mul_f32_e32 v20, v29, v21
	v_mul_f32_e32 v17, v20, v17
	v_mul_f32_e32 v20, 0xbfb8aa3b, v30
	v_exp_f32_e32 v20, v20
	v_mul_f32_e32 v21, 0xbfb8aa3b, v31
	v_exp_f32_e32 v21, v21
	v_cvt_pk_bf16_f32 v16, v16, v17
	v_add_f32_e32 v17, 1.0, v20
	v_rcp_f32_e32 v17, v17
	v_add_f32_e32 v20, 1.0, v21
	v_rcp_f32_e32 v20, v20
	v_pk_mul_f32 v[22:23], v[22:23], v[76:77] op_sel_hi:[1,0]
	v_pk_mul_f32 v[24:25], v[24:25], v[76:77] op_sel_hi:[1,0]
	v_mul_f32_e32 v21, v30, v22
	v_mul_f32_e32 v17, v21, v17
	v_mul_f32_e32 v21, v31, v23
	v_mul_f32_e32 v20, v21, v20
	v_mul_f32_e32 v21, 0xbfb8aa3b, v24
	v_exp_f32_e32 v21, v21
	v_mul_f32_e32 v22, 0xbfb8aa3b, v25
	v_exp_f32_e32 v22, v22
	v_cvt_pk_bf16_f32 v17, v17, v20
	v_add_f32_e32 v20, 1.0, v21
	v_rcp_f32_e32 v20, v20
	v_add_f32_e32 v21, 1.0, v22
	v_rcp_f32_e32 v21, v21
	v_pk_mul_f32 v[26:27], v[26:27], v[76:77] op_sel_hi:[1,0]
	v_mul_f32_e32 v18, v24, v18
	v_mul_f32_e32 v18, v18, v20
	v_mul_f32_e32 v19, v25, v19
	v_mul_f32_e32 v20, 0xbfb8aa3b, v26
	v_mul_f32_e32 v19, v19, v21
	v_exp_f32_e32 v20, v20
	v_mul_f32_e32 v21, 0xbfb8aa3b, v27
	v_exp_f32_e32 v21, v21
	v_cvt_pk_bf16_f32 v18, v18, v19
	v_add_f32_e32 v19, 1.0, v20
	v_rcp_f32_e32 v19, v19
	v_add_f32_e32 v20, 1.0, v21
	v_rcp_f32_e32 v20, v20
	v_mul_f32_e32 v21, v26, v32
	v_mul_f32_e32 v19, v21, v19
	v_mul_f32_e32 v21, v27, v33
	v_mul_f32_e32 v20, v21, v20
	v_cvt_pk_bf16_f32 v19, v19, v20
	v_mad_i64_i32 v[20:21], s[22:23], v66, s68, v[112:113]
	v_lshl_add_u64 v[20:21], v[20:21], 0, v[114:115]
	v_pk_mul_f32 v[12:13], v[12:13], v[68:69] op_sel_hi:[1,0]
	global_store_dwordx4 v[20:21], v[16:19], off
	v_pk_mul_f32 v[4:5], v[4:5], v[68:69] op_sel_hi:[1,0]
	v_pk_mul_f32 v[14:15], v[14:15], v[68:69] op_sel_hi:[1,0]
	v_pk_mul_f32 v[16:17], v[2:3], v[68:69] op_sel_hi:[1,0]
	v_mul_f32_e32 v2, 0xbfb8aa3b, v12
	v_exp_f32_e32 v18, v2
	v_mul_f32_e32 v2, 0xbfb8aa3b, v13
	v_exp_f32_e32 v19, v2
	v_pk_mul_f32 v[2:3], v[0:1], v[68:69] op_sel_hi:[1,0]
	v_add_f32_e32 v0, 1.0, v18
	v_rcp_f32_e32 v0, v0
	v_add_f32_e32 v1, 1.0, v19
	v_rcp_f32_e32 v1, v1
	v_mul_f32_e32 v4, v12, v4
	v_mul_f32_e32 v0, v4, v0
	v_mul_f32_e32 v4, v13, v5
	v_mul_f32_e32 v1, v4, v1
	v_mul_f32_e32 v4, 0xbfb8aa3b, v14
	v_exp_f32_e32 v4, v4
	v_mul_f32_e32 v5, 0xbfb8aa3b, v15
	v_exp_f32_e32 v5, v5
	v_cvt_pk_bf16_f32 v0, v0, v1
	v_add_f32_e32 v1, 1.0, v4
	v_rcp_f32_e32 v1, v1
	v_add_f32_e32 v4, 1.0, v5
	v_rcp_f32_e32 v4, v4
	v_pk_mul_f32 v[6:7], v[6:7], v[68:69] op_sel_hi:[1,0]
	v_pk_mul_f32 v[8:9], v[8:9], v[68:69] op_sel_hi:[1,0]
	v_mul_f32_e32 v5, v14, v6
	v_mul_f32_e32 v1, v5, v1
	v_mul_f32_e32 v5, v15, v7
	v_mul_f32_e32 v4, v5, v4
	v_mul_f32_e32 v5, 0xbfb8aa3b, v8
	v_exp_f32_e32 v5, v5
	v_mul_f32_e32 v6, 0xbfb8aa3b, v9
	v_exp_f32_e32 v6, v6
	v_cvt_pk_bf16_f32 v1, v1, v4
	v_add_f32_e32 v4, 1.0, v5
	v_rcp_f32_e32 v4, v4
	v_add_f32_e32 v5, 1.0, v6
	v_rcp_f32_e32 v5, v5
	v_pk_mul_f32 v[10:11], v[10:11], v[68:69] op_sel_hi:[1,0]
	v_mul_f32_e32 v2, v8, v2
	v_mul_f32_e32 v2, v2, v4
	v_mul_f32_e32 v3, v9, v3
	v_mul_f32_e32 v4, 0xbfb8aa3b, v10
	v_mul_f32_e32 v3, v3, v5
	v_exp_f32_e32 v4, v4
	v_mul_f32_e32 v5, 0xbfb8aa3b, v11
	v_exp_f32_e32 v5, v5
	v_cvt_pk_bf16_f32 v2, v2, v3
	v_add_f32_e32 v3, 1.0, v4
	v_rcp_f32_e32 v3, v3
	v_add_f32_e32 v4, 1.0, v5
	v_rcp_f32_e32 v4, v4
	v_mul_f32_e32 v5, v10, v16
	v_mul_f32_e32 v3, v5, v3
	v_mul_f32_e32 v5, v11, v17
	v_mul_f32_e32 v4, v5, v4
	v_cvt_pk_bf16_f32 v3, v3, v4
	v_mad_i64_i32 v[4:5], s[22:23], v64, s68, v[112:113]
	v_lshl_add_u64 v[4:5], v[4:5], 0, v[114:115]
	global_store_dwordx4 v[4:5], v[0:3], off
	s_cbranch_vccnz .LBB0_875
	s_andn2_b64 vcc, exec, s[4:5]
	s_cbranch_vccnz .LBB0_874
	s_barrier
	s_branch .LBB0_874

.LBB0_2122:
	s_ashr_i32 s13, s12, 31
	s_lshl_b64 s[14:15], s[12:13], 19
	s_add_u32 s14, s60, s14
	s_addc_u32 s15, s61, s15
	s_and_b64 s[16:17], s[0:1], exec
	s_cselect_b32 s13, s15, s21
	s_cselect_b32 s50, s14, s20
	s_ashr_i32 s11, s10, 31
	s_lshl_b64 s[16:17], s[10:11], 19
	s_add_u32 s16, s26, s16
	s_addc_u32 s17, s27, s17
	s_and_b64 s[24:25], s[0:1], exec
	s_cselect_b32 s11, s17, s23
	s_cselect_b32 s51, s16, s22
	s_add_u32 s20, s20, 0x40080
	s_addc_u32 s21, s21, 0
	s_add_u32 s64, s22, 0x100
	v_mov_b32_e32 v0, 0
	s_addc_u32 s65, s23, 0
	s_mov_b32 s66, -2
	v_mov_b32_e32 v1, v0
	v_mov_b32_e32 v2, v0
	v_mov_b32_e32 v3, v0
	v_mov_b32_e32 v4, v0
	v_mov_b32_e32 v5, v0
	v_mov_b32_e32 v6, v0
	v_mov_b32_e32 v7, v0
	v_mov_b32_e32 v16, v0
	v_mov_b32_e32 v17, v0
	v_mov_b32_e32 v18, v0
	v_mov_b32_e32 v19, v0
	v_mov_b32_e32 v20, v0
	v_mov_b32_e32 v21, v0
	v_mov_b32_e32 v22, v0
	v_mov_b32_e32 v23, v0
	v_mov_b32_e32 v32, v0
	v_mov_b32_e32 v33, v0
	v_mov_b32_e32 v34, v0
	v_mov_b32_e32 v35, v0
	s_waitcnt vmcnt(0)
	v_mov_b32_e32 v36, v0
	v_mov_b32_e32 v37, v0
	v_mov_b32_e32 v38, v0
	v_mov_b32_e32 v39, v0
	v_mov_b32_e32 v48, v0
	v_mov_b32_e32 v49, v0
	v_mov_b32_e32 v50, v0
	v_mov_b32_e32 v51, v0
	v_mov_b32_e32 v52, v0
	v_mov_b32_e32 v53, v0
	v_mov_b32_e32 v54, v0
	v_mov_b32_e32 v55, v0
	v_mov_b32_e32 v8, v0
	v_mov_b32_e32 v9, v0
	v_mov_b32_e32 v10, v0
	v_mov_b32_e32 v11, v0
	v_mov_b32_e32 v12, v0
	v_mov_b32_e32 v13, v0
	v_mov_b32_e32 v14, v0
	v_mov_b32_e32 v15, v0
	v_mov_b32_e32 v24, v0
	v_mov_b32_e32 v25, v0
	v_mov_b32_e32 v26, v0
	v_mov_b32_e32 v27, v0
	v_mov_b32_e32 v28, v0
	v_mov_b32_e32 v29, v0
	v_mov_b32_e32 v30, v0
	v_mov_b32_e32 v31, v0
	v_mov_b32_e32 v40, v0
	v_mov_b32_e32 v41, v0
	v_mov_b32_e32 v42, v0
	v_mov_b32_e32 v43, v0
	v_mov_b32_e32 v44, v0
	v_mov_b32_e32 v45, v0
	v_mov_b32_e32 v46, v0
	v_mov_b32_e32 v47, v0
	v_mov_b32_e32 v56, v0
	v_mov_b32_e32 v57, v0
	v_mov_b32_e32 v58, v0
	v_mov_b32_e32 v59, v0
	v_mov_b32_e32 v60, v0
	v_mov_b32_e32 v61, v0
	v_mov_b32_e32 v62, v0
	v_mov_b32_e32 v63, v0
	v_mov_b32_e32 v64, v0
	v_mov_b32_e32 v65, v0
	v_mov_b32_e32 v66, v0
	v_mov_b32_e32 v67, v0
	v_mov_b32_e32 v68, v0
	v_mov_b32_e32 v69, v0
	v_mov_b32_e32 v70, v0
	v_mov_b32_e32 v71, v0
	v_mov_b32_e32 v80, v0
	v_mov_b32_e32 v81, v0
	v_mov_b32_e32 v82, v0
	v_mov_b32_e32 v83, v0
	v_mov_b32_e32 v84, v0
	v_mov_b32_e32 v85, v0
	v_mov_b32_e32 v86, v0
	v_mov_b32_e32 v87, v0
	v_mov_b32_e32 v96, v0
	v_mov_b32_e32 v97, v0
	v_mov_b32_e32 v98, v0
	v_mov_b32_e32 v99, v0
	v_mov_b32_e32 v100, v0
	v_mov_b32_e32 v101, v0
	v_mov_b32_e32 v102, v0
	v_mov_b32_e32 v103, v0
	v_mov_b32_e32 v112, v0
	v_mov_b32_e32 v113, v0
	v_mov_b32_e32 v114, v0
	v_mov_b32_e32 v115, v0
	v_mov_b32_e32 v116, v0
	v_mov_b32_e32 v117, v0
	v_mov_b32_e32 v118, v0
	v_mov_b32_e32 v119, v0
	v_mov_b32_e32 v72, v0
	v_mov_b32_e32 v73, v0
	v_mov_b32_e32 v74, v0
	v_mov_b32_e32 v75, v0
	v_mov_b32_e32 v76, v0
	v_mov_b32_e32 v77, v0
	v_mov_b32_e32 v78, v0
	v_mov_b32_e32 v79, v0
	v_mov_b32_e32 v88, v0
	v_mov_b32_e32 v89, v0
	v_mov_b32_e32 v90, v0
	v_mov_b32_e32 v91, v0
	v_mov_b32_e32 v92, v0
	v_mov_b32_e32 v93, v0
	v_mov_b32_e32 v94, v0
	v_mov_b32_e32 v95, v0
	v_mov_b32_e32 v104, v0
	v_mov_b32_e32 v105, v0
	v_mov_b32_e32 v106, v0
	v_mov_b32_e32 v107, v0
	v_mov_b32_e32 v108, v0
	v_mov_b32_e32 v109, v0
	v_mov_b32_e32 v110, v0
	v_mov_b32_e32 v111, v0
	v_mov_b32_e32 v120, v0
	v_mov_b32_e32 v121, v0
	v_mov_b32_e32 v122, v0
	v_mov_b32_e32 v123, v0
	v_mov_b32_e32 v124, v0
	v_mov_b32_e32 v125, v0
	v_mov_b32_e32 v126, v0
	v_mov_b32_e32 v127, v0
	s_lshl_b32 s97, s18, 8
	v_add_u32_e32 v252, s97, v149
	v_mov_b32_e32 v253, 0
	v_lshlrev_b64 v[252:253], 6, v[252:253]
	v_lshl_add_u64 v[254:255], v[136:137], 0, v[252:253]
	global_load_dwordx4 v[236:239], v[254:255], off
	global_load_dwordx4 v[240:243], v[254:255], off offset:1024
	global_load_dwordx4 v[244:247], v[254:255], off offset:2048
	global_load_dwordx4 v[248:251], v[254:255], off offset:3072

.LBB0_2126:
	s_lshl_b32 s11, s18, 8
	v_add_u32_e32 v146, s11, v149
	v_or_b32_e32 v162, 16, v146
	v_ashrrev_i32_e32 v147, 31, v146
	v_ashrrev_i32_e32 v163, 31, v162
	v_lshlrev_b64 v[160:161], 6, v[146:147]
	v_lshlrev_b64 v[162:163], 6, v[162:163]
	v_lshl_add_u64 v[160:161], v[136:137], 0, v[160:161]
	v_lshl_add_u64 v[166:167], v[136:137], 0, v[162:163]
	v_mov_b32_e32 v162, v236
	v_mov_b32_e32 v163, v237
	v_mov_b32_e32 v164, v238
	v_mov_b32_e32 v165, v239
	v_mov_b32_e32 v166, v240
	v_mov_b32_e32 v167, v241
	v_mov_b32_e32 v168, v242
	v_mov_b32_e32 v169, v243
	v_or_b32_e32 v160, 32, v146
	v_ashrrev_i32_e32 v161, 31, v160
	v_lshlrev_b64 v[160:161], 6, v[160:161]
	v_lshl_add_u64 v[160:161], v[136:137], 0, v[160:161]
	v_mov_b32_e32 v170, v244
	v_mov_b32_e32 v171, v245
	v_mov_b32_e32 v172, v246
	v_mov_b32_e32 v173, v247
	v_or_b32_e32 v160, 48, v146
	v_ashrrev_i32_e32 v161, 31, v160
	v_lshlrev_b64 v[160:161], 6, v[160:161]
	v_lshl_add_u64 v[160:161], v[136:137], 0, v[160:161]
	v_mov_b32_e32 v174, v248
	v_mov_b32_e32 v175, v249
	v_mov_b32_e32 v176, v250
	v_mov_b32_e32 v177, v251
	v_and_b32_e32 v148, 64, v158
	v_xor_b32_e32 v147, 16, v158
	v_add_u32_e32 v148, 64, v148
	v_xor_b32_e32 v160, 32, v158
	v_cmp_lt_i32_e32 vcc, v147, v148
	v_lshl_or_b32 v178, s49, 7, v154
	v_ashrrev_i32_e32 v179, 31, v178
	v_cndmask_b32_e32 v147, v158, v147, vcc
	v_cmp_lt_i32_e32 vcc, v160, v148
	v_mov_b32_e32 v180, v163
	v_mov_b32_e32 v181, v164
	v_mov_b32_e32 v163, v165
	v_cndmask_b32_e32 v148, v158, v160, vcc
	v_pk_add_f32 v[162:163], v[180:181], v[162:163]
	v_lshlrev_b32_e32 v160, 2, v147
	v_lshlrev_b32_e32 v147, 2, v148
	v_mov_b32_e32 v164, v167
	v_mov_b32_e32 v165, v168
	v_mov_b32_e32 v167, v169
	v_add_f32_e32 v148, v162, v163
	v_mov_b32_e32 v168, v171
	v_mov_b32_e32 v169, v172
	v_mov_b32_e32 v171, v173
	v_pk_add_f32 v[162:163], v[164:165], v[166:167]
	ds_bpermute_b32 v161, v160, v148
	v_mov_b32_e32 v172, v175
	v_mov_b32_e32 v173, v176
	v_mov_b32_e32 v175, v177
	v_pk_add_f32 v[164:165], v[168:169], v[170:171]
	v_add_f32_e32 v162, v162, v163
	v_pk_add_f32 v[166:167], v[172:173], v[174:175]
	v_add_f32_e32 v163, v164, v165
	ds_bpermute_b32 v165, v160, v162
	v_add_f32_e32 v164, v166, v167
	ds_bpermute_b32 v166, v160, v163
	ds_bpermute_b32 v167, v160, v164
	s_waitcnt lgkmcnt(3)
	v_add_f32_e32 v148, v148, v161
	ds_bpermute_b32 v161, v147, v148
	s_waitcnt lgkmcnt(3)
	v_add_f32_e32 v162, v162, v165
	ds_bpermute_b32 v165, v147, v162
	s_waitcnt lgkmcnt(3)
	v_add_f32_e32 v163, v163, v166
	s_waitcnt lgkmcnt(2)
	v_add_f32_e32 v164, v164, v167
	ds_bpermute_b32 v166, v147, v163
	ds_bpermute_b32 v167, v147, v164
	s_waitcnt lgkmcnt(3)
	v_add_f32_e32 v148, v148, v161
	v_fmamk_f32 v148, v148, 0x3a800000, v159
	s_waitcnt lgkmcnt(2)
	v_add_f32_e32 v161, v162, v165
	v_rsq_f32_e32 v162, v148
	s_waitcnt lgkmcnt(1)
	v_add_f32_e32 v163, v163, v166
	s_waitcnt lgkmcnt(0)
	v_add_f32_e32 v164, v164, v167
	v_fmamk_f32 v148, v161, 0x3a800000, v159
	v_fmamk_f32 v161, v163, 0x3a800000, v159
	v_fmamk_f32 v163, v164, 0x3a800000, v159
	v_pk_mul_f32 v[126:127], v[126:127], v[162:163] op_sel_hi:[1,0]
	v_pk_mul_f32 v[124:125], v[124:125], v[162:163] op_sel_hi:[1,0]
	v_pk_mul_f32 v[118:119], v[118:119], v[162:163] op_sel_hi:[1,0]
	v_pk_mul_f32 v[116:117], v[116:117], v[162:163] op_sel_hi:[1,0]
	v_mul_f32_e32 v118, v126, v118
	v_mul_f32_e32 v116, v124, v116
	v_mul_f32_e32 v124, 0xbfb8aa3b, v124
	v_mul_f32_e32 v117, v125, v117
	v_mul_f32_e32 v125, 0xbfb8aa3b, v125
	v_mul_f32_e32 v126, 0xbfb8aa3b, v126
	v_mul_f32_e32 v119, v127, v119
	v_mul_f32_e32 v127, 0xbfb8aa3b, v127
	v_exp_f32_e32 v124, v124
	v_exp_f32_e32 v125, v125
	v_exp_f32_e32 v126, v126
	v_exp_f32_e32 v127, v127
	v_pk_mul_f32 v[120:121], v[120:121], v[162:163] op_sel_hi:[1,0]
	v_pk_mul_f32 v[122:123], v[122:123], v[162:163] op_sel_hi:[1,0]
	v_pk_mul_f32 v[114:115], v[114:115], v[162:163] op_sel_hi:[1,0]
	v_pk_mul_f32 v[112:113], v[112:113], v[162:163] op_sel_hi:[1,0]
	v_mul_f32_e32 v162, 0xbfb8aa3b, v121
	v_add_f32_e32 v124, 1.0, v124
	v_add_f32_e32 v125, 1.0, v125
	v_add_f32_e32 v126, 1.0, v126
	v_exp_f32_e32 v162, v162
	v_add_f32_e32 v127, 1.0, v127
	v_rcp_f32_e32 v124, v124
	v_rcp_f32_e32 v125, v125
	v_rcp_f32_e32 v126, v126
	v_rcp_f32_e32 v127, v127
	v_rsq_f32_e32 v166, v161
	v_mul_f32_e32 v161, 0xbfb8aa3b, v120
	v_exp_f32_e32 v161, v161
	v_add_f32_e32 v162, 1.0, v162
	v_mul_f32_e32 v116, v116, v124
	v_mul_f32_e32 v117, v117, v125
	v_mul_f32_e32 v118, v118, v126
	v_mul_f32_e32 v119, v119, v127
	v_cvt_pk_bf16_f32 v116, v116, v117
	v_cvt_pk_bf16_f32 v117, v118, v119
	v_rcp_f32_e32 v118, v162
	v_add_f32_e32 v161, 1.0, v161
	v_mul_f32_e32 v113, v121, v113
	v_rcp_f32_e32 v161, v161
	v_mul_f32_e32 v113, v113, v118
	v_mul_f32_e32 v118, 0xbfb8aa3b, v122
	v_exp_f32_e32 v119, v118
	v_mul_f32_e32 v118, 0xbfb8aa3b, v123
	v_mul_f32_e32 v112, v120, v112
	v_exp_f32_e32 v120, v118
	v_mul_f32_e32 v112, v112, v161
	v_cvt_pk_bf16_f32 v118, v112, v113
	v_add_f32_e32 v112, 1.0, v119
	v_rcp_f32_e32 v112, v112
	v_add_f32_e32 v113, 1.0, v120
	v_rcp_f32_e32 v113, v113
	v_mul_f32_e32 v114, v122, v114
	v_rsq_f32_e32 v164, v148
	v_mul_f32_e32 v112, v114, v112
	v_mul_f32_e32 v114, v123, v115
	v_mul_f32_e32 v113, v114, v113
	v_cvt_pk_bf16_f32 v119, v112, v113
	v_mov_b64_e32 v[112:113], s[36:37]
	v_mad_i64_i32 v[120:121], s[20:21], v146, s48, v[112:113]
	v_lshlrev_b64 v[114:115], 1, v[178:179]
	v_lshl_add_u64 v[120:121], v[120:121], 0, v[114:115]
	v_pk_mul_f32 v[108:109], v[108:109], v[164:165] op_sel_hi:[1,0]
	global_store_dwordx4 v[120:121], v[116:119], off
	v_pk_mul_f32 v[100:101], v[100:101], v[164:165] op_sel_hi:[1,0]
	v_pk_mul_f32 v[110:111], v[110:111], v[164:165] op_sel_hi:[1,0]
	v_pk_mul_f32 v[116:117], v[98:99], v[164:165] op_sel_hi:[1,0]
	v_mul_f32_e32 v98, 0xbfb8aa3b, v108
	v_exp_f32_e32 v119, v98
	v_mul_f32_e32 v98, 0xbfb8aa3b, v109
	v_exp_f32_e32 v120, v98
	v_pk_mul_f32 v[98:99], v[96:97], v[164:165] op_sel_hi:[1,0]
	v_add_f32_e32 v96, 1.0, v119
	v_rcp_f32_e32 v96, v96
	v_add_f32_e32 v97, 1.0, v120
	v_rcp_f32_e32 v97, v97
	v_mul_f32_e32 v100, v108, v100
	v_mul_f32_e32 v96, v100, v96
	v_mul_f32_e32 v100, v109, v101
	v_mul_f32_e32 v97, v100, v97
	v_mul_f32_e32 v100, 0xbfb8aa3b, v110
	v_exp_f32_e32 v100, v100
	v_mul_f32_e32 v101, 0xbfb8aa3b, v111
	v_exp_f32_e32 v101, v101
	v_cvt_pk_bf16_f32 v96, v96, v97
	v_add_f32_e32 v97, 1.0, v100
	v_rcp_f32_e32 v97, v97
	v_add_f32_e32 v100, 1.0, v101
	v_rcp_f32_e32 v100, v100
	v_pk_mul_f32 v[102:103], v[102:103], v[164:165] op_sel_hi:[1,0]
	v_pk_mul_f32 v[104:105], v[104:105], v[164:165] op_sel_hi:[1,0]
	v_mul_f32_e32 v101, v110, v102
	v_mul_f32_e32 v97, v101, v97
	v_mul_f32_e32 v101, v111, v103
	v_mul_f32_e32 v100, v101, v100
	v_mul_f32_e32 v101, 0xbfb8aa3b, v104
	v_exp_f32_e32 v101, v101
	v_mul_f32_e32 v102, 0xbfb8aa3b, v105
	v_exp_f32_e32 v102, v102
	v_cvt_pk_bf16_f32 v97, v97, v100
	v_add_f32_e32 v100, 1.0, v101
	v_rcp_f32_e32 v100, v100
	v_add_f32_e32 v101, 1.0, v102
	v_rcp_f32_e32 v101, v101
	v_pk_mul_f32 v[106:107], v[106:107], v[164:165] op_sel_hi:[1,0]
	v_mul_f32_e32 v98, v104, v98
	v_mul_f32_e32 v98, v98, v100
	v_mul_f32_e32 v99, v105, v99
	v_mul_f32_e32 v100, 0xbfb8aa3b, v106
	v_mul_f32_e32 v99, v99, v101
	v_exp_f32_e32 v100, v100
	v_mul_f32_e32 v101, 0xbfb8aa3b, v107
	v_exp_f32_e32 v101, v101
	v_cvt_pk_bf16_f32 v98, v98, v99
	v_add_f32_e32 v99, 1.0, v100
	v_rcp_f32_e32 v99, v99
	v_add_f32_e32 v100, 1.0, v101
	v_rcp_f32_e32 v100, v100
	v_mul_f32_e32 v101, v106, v116
	v_mul_f32_e32 v99, v101, v99
	v_mul_f32_e32 v101, v107, v117
	v_add_u32_e32 v118, s11, v151
	v_mul_f32_e32 v100, v101, v100
	v_cvt_pk_bf16_f32 v99, v99, v100
	v_mad_i64_i32 v[100:101], s[20:21], v118, s48, v[112:113]
	v_lshl_add_u64 v[100:101], v[100:101], 0, v[114:115]
	v_pk_mul_f32 v[92:93], v[92:93], v[166:167] op_sel_hi:[1,0]
	global_store_dwordx4 v[100:101], v[96:99], off
	v_pk_mul_f32 v[84:85], v[84:85], v[166:167] op_sel_hi:[1,0]
	v_pk_mul_f32 v[94:95], v[94:95], v[166:167] op_sel_hi:[1,0]
	v_pk_mul_f32 v[96:97], v[82:83], v[166:167] op_sel_hi:[1,0]
	v_mul_f32_e32 v82, 0xbfb8aa3b, v92
	v_exp_f32_e32 v99, v82
	v_mul_f32_e32 v82, 0xbfb8aa3b, v93
	v_exp_f32_e32 v100, v82
	v_pk_mul_f32 v[82:83], v[80:81], v[166:167] op_sel_hi:[1,0]
	v_add_f32_e32 v80, 1.0, v99
	v_rcp_f32_e32 v80, v80
	v_add_f32_e32 v81, 1.0, v100
	v_rcp_f32_e32 v81, v81
	v_mul_f32_e32 v84, v92, v84
	v_mul_f32_e32 v80, v84, v80
	v_mul_f32_e32 v84, v93, v85
	v_mul_f32_e32 v81, v84, v81
	v_mul_f32_e32 v84, 0xbfb8aa3b, v94
	v_exp_f32_e32 v84, v84
	v_mul_f32_e32 v85, 0xbfb8aa3b, v95
	v_exp_f32_e32 v85, v85
	v_cvt_pk_bf16_f32 v80, v80, v81
	v_add_f32_e32 v81, 1.0, v84
	v_rcp_f32_e32 v81, v81
	v_add_f32_e32 v84, 1.0, v85
	v_rcp_f32_e32 v84, v84
	v_pk_mul_f32 v[86:87], v[86:87], v[166:167] op_sel_hi:[1,0]
	v_pk_mul_f32 v[88:89], v[88:89], v[166:167] op_sel_hi:[1,0]
	v_mul_f32_e32 v85, v94, v86
	v_mul_f32_e32 v81, v85, v81
	v_mul_f32_e32 v85, v95, v87
	v_mul_f32_e32 v84, v85, v84
	v_mul_f32_e32 v85, 0xbfb8aa3b, v88
	v_exp_f32_e32 v85, v85
	v_mul_f32_e32 v86, 0xbfb8aa3b, v89
	v_exp_f32_e32 v86, v86
	v_cvt_pk_bf16_f32 v81, v81, v84
	v_add_f32_e32 v84, 1.0, v85
	v_rcp_f32_e32 v84, v84
	v_add_f32_e32 v85, 1.0, v86
	v_rcp_f32_e32 v85, v85
	v_pk_mul_f32 v[90:91], v[90:91], v[166:167] op_sel_hi:[1,0]
	v_mul_f32_e32 v82, v88, v82
	v_mul_f32_e32 v82, v82, v84
	v_mul_f32_e32 v83, v89, v83
	v_mul_f32_e32 v84, 0xbfb8aa3b, v90
	v_mul_f32_e32 v83, v83, v85
	v_exp_f32_e32 v84, v84
	v_mul_f32_e32 v85, 0xbfb8aa3b, v91
	v_exp_f32_e32 v85, v85
	v_cvt_pk_bf16_f32 v82, v82, v83
	v_add_f32_e32 v83, 1.0, v84
	v_rcp_f32_e32 v83, v83
	v_add_f32_e32 v84, 1.0, v85
	v_rcp_f32_e32 v84, v84
	v_rsq_f32_e32 v148, v163
	v_mul_f32_e32 v85, v90, v96
	v_mul_f32_e32 v83, v85, v83
	v_mul_f32_e32 v85, v91, v97
	v_add_u32_e32 v98, s11, v152
	v_mul_f32_e32 v84, v85, v84
	v_cvt_pk_bf16_f32 v83, v83, v84
	v_mad_i64_i32 v[84:85], s[20:21], v98, s48, v[112:113]
	v_lshl_add_u64 v[84:85], v[84:85], 0, v[114:115]
	v_pk_mul_f32 v[76:77], v[76:77], v[148:149] op_sel_hi:[1,0]
	global_store_dwordx4 v[84:85], v[80:83], off
	v_pk_mul_f32 v[68:69], v[68:69], v[148:149] op_sel_hi:[1,0]
	v_pk_mul_f32 v[78:79], v[78:79], v[148:149] op_sel_hi:[1,0]
	v_pk_mul_f32 v[80:81], v[66:67], v[148:149] op_sel_hi:[1,0]
	v_mul_f32_e32 v66, 0xbfb8aa3b, v76
	v_exp_f32_e32 v83, v66
	v_mul_f32_e32 v66, 0xbfb8aa3b, v77
	v_exp_f32_e32 v84, v66
	v_pk_mul_f32 v[66:67], v[64:65], v[148:149] op_sel_hi:[1,0]
	v_add_f32_e32 v64, 1.0, v83
	v_rcp_f32_e32 v64, v64
	v_add_f32_e32 v65, 1.0, v84
	v_rcp_f32_e32 v65, v65
	v_mul_f32_e32 v68, v76, v68
	v_mul_f32_e32 v64, v68, v64
	v_mul_f32_e32 v68, v77, v69
	v_mul_f32_e32 v65, v68, v65
	v_mul_f32_e32 v68, 0xbfb8aa3b, v78
	v_exp_f32_e32 v68, v68
	v_mul_f32_e32 v69, 0xbfb8aa3b, v79
	v_exp_f32_e32 v69, v69
	v_cvt_pk_bf16_f32 v64, v64, v65
	v_add_f32_e32 v65, 1.0, v68
	v_rcp_f32_e32 v65, v65
	v_add_f32_e32 v68, 1.0, v69
	v_rcp_f32_e32 v68, v68
	v_pk_mul_f32 v[70:71], v[70:71], v[148:149] op_sel_hi:[1,0]
	v_pk_mul_f32 v[72:73], v[72:73], v[148:149] op_sel_hi:[1,0]
	v_mul_f32_e32 v69, v78, v70
	v_mul_f32_e32 v65, v69, v65
	v_mul_f32_e32 v69, v79, v71
	v_mul_f32_e32 v68, v69, v68
	v_mul_f32_e32 v69, 0xbfb8aa3b, v72
	v_exp_f32_e32 v69, v69
	v_mul_f32_e32 v70, 0xbfb8aa3b, v73
	v_exp_f32_e32 v70, v70
	v_cvt_pk_bf16_f32 v65, v65, v68
	v_add_f32_e32 v68, 1.0, v69
	v_rcp_f32_e32 v68, v68
	v_add_f32_e32 v69, 1.0, v70
	v_rcp_f32_e32 v69, v69
	v_pk_mul_f32 v[74:75], v[74:75], v[148:149] op_sel_hi:[1,0]
	v_mul_f32_e32 v66, v72, v66
	v_mul_f32_e32 v66, v66, v68
	v_mul_f32_e32 v67, v73, v67
	v_mul_f32_e32 v68, 0xbfb8aa3b, v74
	v_mul_f32_e32 v67, v67, v69
	v_exp_f32_e32 v68, v68
	v_mul_f32_e32 v69, 0xbfb8aa3b, v75
	v_exp_f32_e32 v69, v69
	v_cvt_pk_bf16_f32 v66, v66, v67
	v_add_f32_e32 v67, 1.0, v68
	v_rcp_f32_e32 v67, v67
	v_add_f32_e32 v68, 1.0, v69
	v_rcp_f32_e32 v68, v68
	v_mul_f32_e32 v69, v74, v80
	v_mul_f32_e32 v67, v69, v67
	v_mul_f32_e32 v69, v75, v81
	v_add_u32_e32 v82, s11, v153
	v_mul_f32_e32 v68, v69, v68
	v_cvt_pk_bf16_f32 v67, v67, v68
	v_mad_i64_i32 v[68:69], s[20:21], v82, s48, v[112:113]
	v_add_u32_e32 v88, 0x80, v146
	v_lshl_add_u64 v[68:69], v[68:69], 0, v[114:115]
	v_ashrrev_i32_e32 v89, 31, v88
	global_store_dwordx4 v[68:69], v[64:67], off
	v_add_u32_e32 v70, 0x90, v146
	v_ashrrev_i32_e32 v71, 31, v70
	v_lshlrev_b64 v[64:65], 6, v[88:89]
	v_lshl_add_u64 v[64:65], v[136:137], 0, v[64:65]
	global_load_dwordx4 v[72:75], v[64:65], off
	v_lshlrev_b64 v[64:65], 6, v[70:71]
	v_lshl_add_u64 v[64:65], v[136:137], 0, v[64:65]
	global_load_dwordx4 v[76:79], v[64:65], off
	v_add_u32_e32 v66, 0xa0, v146
	v_ashrrev_i32_e32 v67, 31, v66
	v_lshlrev_b64 v[64:65], 6, v[66:67]
	v_lshl_add_u64 v[64:65], v[136:137], 0, v[64:65]
	global_load_dwordx4 v[80:83], v[64:65], off
	v_add_u32_e32 v64, 0xb0, v146
	v_ashrrev_i32_e32 v65, 31, v64
	v_lshlrev_b64 v[68:69], 6, v[64:65]
	v_lshl_add_u64 v[68:69], v[136:137], 0, v[68:69]
	global_load_dwordx4 v[84:87], v[68:69], off
	s_andn2_b64 vcc, exec, s[0:1]
	s_mov_b64 s[0:1], -1
	s_waitcnt vmcnt(3)
	v_mov_b32_e32 v68, v73
	v_mov_b32_e32 v69, v74
	v_mov_b32_e32 v73, v75
	v_pk_add_f32 v[68:69], v[68:69], v[72:73]
	s_nop 0
	v_add_f32_e32 v65, v68, v69
	ds_bpermute_b32 v67, v160, v65
	s_waitcnt vmcnt(2)
	v_mov_b32_e32 v68, v77
	v_mov_b32_e32 v69, v78
	v_mov_b32_e32 v77, v79
	v_pk_add_f32 v[68:69], v[68:69], v[76:77]
	s_waitcnt lgkmcnt(0)
	v_add_f32_e32 v65, v65, v67
	ds_bpermute_b32 v67, v147, v65
	v_add_f32_e32 v68, v68, v69
	ds_bpermute_b32 v69, v160, v68
	s_waitcnt lgkmcnt(1)
	v_add_f32_e32 v65, v65, v67
	v_fmamk_f32 v65, v65, 0x3a800000, v159
	v_rsq_f32_e32 v72, v65
	s_waitcnt lgkmcnt(0)
	v_add_f32_e32 v65, v68, v69
	s_waitcnt vmcnt(1)
	v_mov_b32_e32 v68, v81
	v_mov_b32_e32 v69, v82
	v_mov_b32_e32 v81, v83
	v_pk_add_f32 v[68:69], v[68:69], v[80:81]
	ds_bpermute_b32 v67, v147, v65
	v_add_f32_e32 v71, v68, v69
	s_waitcnt vmcnt(0)
	v_mov_b32_e32 v68, v85
	v_mov_b32_e32 v69, v86
	v_mov_b32_e32 v85, v87
	ds_bpermute_b32 v73, v160, v71
	v_pk_add_f32 v[68:69], v[68:69], v[84:85]
	s_waitcnt lgkmcnt(1)
	v_add_f32_e32 v65, v65, v67
	v_add_f32_e32 v68, v68, v69
	ds_bpermute_b32 v69, v160, v68
	s_waitcnt lgkmcnt(1)
	v_add_f32_e32 v67, v71, v73
	ds_bpermute_b32 v71, v147, v67
	v_fmamk_f32 v65, v65, 0x3a800000, v159
	v_rsq_f32_e32 v74, v65
	s_waitcnt lgkmcnt(1)
	v_add_f32_e32 v68, v68, v69
	ds_bpermute_b32 v69, v147, v68
	s_waitcnt lgkmcnt(1)
	v_add_f32_e32 v65, v67, v71
	v_fmamk_f32 v65, v65, 0x3a800000, v159
	v_rsq_f32_e32 v76, v65
	v_pk_mul_f32 v[60:61], v[60:61], v[72:73] op_sel_hi:[1,0]
	s_waitcnt lgkmcnt(0)
	v_add_f32_e32 v65, v68, v69
	v_fmamk_f32 v65, v65, 0x3a800000, v159
	v_pk_mul_f32 v[78:79], v[50:51], v[72:73] op_sel_hi:[1,0]
	v_mul_f32_e32 v50, 0xbfb8aa3b, v60
	v_rsq_f32_e32 v68, v65
	v_exp_f32_e32 v65, v50
	v_mul_f32_e32 v50, 0xbfb8aa3b, v61
	v_exp_f32_e32 v67, v50
	v_pk_mul_f32 v[50:51], v[48:49], v[72:73] op_sel_hi:[1,0]
	v_add_f32_e32 v48, 1.0, v65
	v_rcp_f32_e32 v48, v48
	v_add_f32_e32 v49, 1.0, v67
	v_rcp_f32_e32 v49, v49
	v_pk_mul_f32 v[52:53], v[52:53], v[72:73] op_sel_hi:[1,0]
	v_pk_mul_f32 v[62:63], v[62:63], v[72:73] op_sel_hi:[1,0]
	v_mul_f32_e32 v52, v60, v52
	v_mul_f32_e32 v48, v52, v48
	v_mul_f32_e32 v52, v61, v53
	v_mul_f32_e32 v49, v52, v49
	v_mul_f32_e32 v52, 0xbfb8aa3b, v62
	v_exp_f32_e32 v52, v52
	v_mul_f32_e32 v53, 0xbfb8aa3b, v63
	v_exp_f32_e32 v53, v53
	v_cvt_pk_bf16_f32 v48, v48, v49
	v_add_f32_e32 v49, 1.0, v52
	v_rcp_f32_e32 v49, v49
	v_add_f32_e32 v52, 1.0, v53
	v_rcp_f32_e32 v52, v52
	v_pk_mul_f32 v[54:55], v[54:55], v[72:73] op_sel_hi:[1,0]
	v_pk_mul_f32 v[56:57], v[56:57], v[72:73] op_sel_hi:[1,0]
	v_mul_f32_e32 v53, v62, v54
	v_mul_f32_e32 v49, v53, v49
	v_mul_f32_e32 v53, v63, v55
	v_mul_f32_e32 v52, v53, v52
	v_mul_f32_e32 v53, 0xbfb8aa3b, v56
	v_exp_f32_e32 v53, v53
	v_mul_f32_e32 v54, 0xbfb8aa3b, v57
	v_exp_f32_e32 v54, v54
	v_cvt_pk_bf16_f32 v49, v49, v52
	v_add_f32_e32 v52, 1.0, v53
	v_rcp_f32_e32 v52, v52
	v_add_f32_e32 v53, 1.0, v54
	v_rcp_f32_e32 v53, v53
	v_pk_mul_f32 v[58:59], v[58:59], v[72:73] op_sel_hi:[1,0]
	v_mul_f32_e32 v50, v56, v50
	v_mul_f32_e32 v50, v50, v52
	v_mul_f32_e32 v51, v57, v51
	v_mul_f32_e32 v52, 0xbfb8aa3b, v58
	v_mul_f32_e32 v51, v51, v53
	v_exp_f32_e32 v52, v52
	v_mul_f32_e32 v53, 0xbfb8aa3b, v59
	v_exp_f32_e32 v53, v53
	v_cvt_pk_bf16_f32 v50, v50, v51
	v_add_f32_e32 v51, 1.0, v52
	v_rcp_f32_e32 v51, v51
	v_add_f32_e32 v52, 1.0, v53
	v_rcp_f32_e32 v52, v52
	v_mul_f32_e32 v53, v58, v78
	v_mul_f32_e32 v51, v53, v51
	v_mul_f32_e32 v53, v59, v79
	v_mul_f32_e32 v52, v53, v52
	v_cvt_pk_bf16_f32 v51, v51, v52
	v_mad_i64_i32 v[52:53], s[20:21], v88, s48, v[112:113]
	v_lshl_add_u64 v[52:53], v[52:53], 0, v[114:115]
	v_pk_mul_f32 v[44:45], v[44:45], v[74:75] op_sel_hi:[1,0]
	global_store_dwordx4 v[52:53], v[48:51], off
	v_pk_mul_f32 v[36:37], v[36:37], v[74:75] op_sel_hi:[1,0]
	v_pk_mul_f32 v[46:47], v[46:47], v[74:75] op_sel_hi:[1,0]
	v_pk_mul_f32 v[48:49], v[34:35], v[74:75] op_sel_hi:[1,0]
	v_mul_f32_e32 v34, 0xbfb8aa3b, v44
	v_exp_f32_e32 v50, v34
	v_mul_f32_e32 v34, 0xbfb8aa3b, v45
	v_exp_f32_e32 v51, v34
	v_pk_mul_f32 v[34:35], v[32:33], v[74:75] op_sel_hi:[1,0]
	v_add_f32_e32 v32, 1.0, v50
	v_rcp_f32_e32 v32, v32
	v_add_f32_e32 v33, 1.0, v51
	v_rcp_f32_e32 v33, v33
	v_mul_f32_e32 v36, v44, v36
	v_mul_f32_e32 v32, v36, v32
	v_mul_f32_e32 v36, v45, v37
	v_mul_f32_e32 v33, v36, v33
	v_mul_f32_e32 v36, 0xbfb8aa3b, v46
	v_exp_f32_e32 v36, v36
	v_mul_f32_e32 v37, 0xbfb8aa3b, v47
	v_exp_f32_e32 v37, v37
	v_cvt_pk_bf16_f32 v32, v32, v33
	v_add_f32_e32 v33, 1.0, v36
	v_rcp_f32_e32 v33, v33
	v_add_f32_e32 v36, 1.0, v37
	v_rcp_f32_e32 v36, v36
	v_pk_mul_f32 v[38:39], v[38:39], v[74:75] op_sel_hi:[1,0]
	v_pk_mul_f32 v[40:41], v[40:41], v[74:75] op_sel_hi:[1,0]
	v_mul_f32_e32 v37, v46, v38
	v_mul_f32_e32 v33, v37, v33
	v_mul_f32_e32 v37, v47, v39
	v_mul_f32_e32 v36, v37, v36
	v_mul_f32_e32 v37, 0xbfb8aa3b, v40
	v_exp_f32_e32 v37, v37
	v_mul_f32_e32 v38, 0xbfb8aa3b, v41
	v_exp_f32_e32 v38, v38
	v_cvt_pk_bf16_f32 v33, v33, v36
	v_add_f32_e32 v36, 1.0, v37
	v_rcp_f32_e32 v36, v36
	v_add_f32_e32 v37, 1.0, v38
	v_rcp_f32_e32 v37, v37
	v_pk_mul_f32 v[42:43], v[42:43], v[74:75] op_sel_hi:[1,0]
	v_mul_f32_e32 v34, v40, v34
	v_mul_f32_e32 v34, v34, v36
	v_mul_f32_e32 v35, v41, v35
	v_mul_f32_e32 v36, 0xbfb8aa3b, v42
	v_mul_f32_e32 v35, v35, v37
	v_exp_f32_e32 v36, v36
	v_mul_f32_e32 v37, 0xbfb8aa3b, v43
	v_exp_f32_e32 v37, v37
	v_cvt_pk_bf16_f32 v34, v34, v35
	v_add_f32_e32 v35, 1.0, v36
	v_rcp_f32_e32 v35, v35
	v_add_f32_e32 v36, 1.0, v37
	v_rcp_f32_e32 v36, v36
	v_mul_f32_e32 v37, v42, v48
	v_mul_f32_e32 v35, v37, v35
	v_mul_f32_e32 v37, v43, v49
	v_mul_f32_e32 v36, v37, v36
	v_cvt_pk_bf16_f32 v35, v35, v36
	v_mad_i64_i32 v[36:37], s[20:21], v70, s48, v[112:113]
	v_lshl_add_u64 v[36:37], v[36:37], 0, v[114:115]
	v_pk_mul_f32 v[28:29], v[28:29], v[76:77] op_sel_hi:[1,0]
	global_store_dwordx4 v[36:37], v[32:35], off
	v_pk_mul_f32 v[20:21], v[20:21], v[76:77] op_sel_hi:[1,0]
	v_pk_mul_f32 v[30:31], v[30:31], v[76:77] op_sel_hi:[1,0]
	v_pk_mul_f32 v[32:33], v[18:19], v[76:77] op_sel_hi:[1,0]
	v_mul_f32_e32 v18, 0xbfb8aa3b, v28
	v_exp_f32_e32 v34, v18
	v_mul_f32_e32 v18, 0xbfb8aa3b, v29
	v_exp_f32_e32 v35, v18
	v_pk_mul_f32 v[18:19], v[16:17], v[76:77] op_sel_hi:[1,0]
	v_add_f32_e32 v16, 1.0, v34
	v_rcp_f32_e32 v16, v16
	v_add_f32_e32 v17, 1.0, v35
	v_rcp_f32_e32 v17, v17
	v_mul_f32_e32 v20, v28, v20
	v_mul_f32_e32 v16, v20, v16
	v_mul_f32_e32 v20, v29, v21
	v_mul_f32_e32 v17, v20, v17
	v_mul_f32_e32 v20, 0xbfb8aa3b, v30
	v_exp_f32_e32 v20, v20
	v_mul_f32_e32 v21, 0xbfb8aa3b, v31
	v_exp_f32_e32 v21, v21
	v_cvt_pk_bf16_f32 v16, v16, v17
	v_add_f32_e32 v17, 1.0, v20
	v_rcp_f32_e32 v17, v17
	v_add_f32_e32 v20, 1.0, v21
	v_rcp_f32_e32 v20, v20
	v_pk_mul_f32 v[22:23], v[22:23], v[76:77] op_sel_hi:[1,0]
	v_pk_mul_f32 v[24:25], v[24:25], v[76:77] op_sel_hi:[1,0]
	v_mul_f32_e32 v21, v30, v22
	v_mul_f32_e32 v17, v21, v17
	v_mul_f32_e32 v21, v31, v23
	v_mul_f32_e32 v20, v21, v20
	v_mul_f32_e32 v21, 0xbfb8aa3b, v24
	v_exp_f32_e32 v21, v21
	v_mul_f32_e32 v22, 0xbfb8aa3b, v25
	v_exp_f32_e32 v22, v22
	v_cvt_pk_bf16_f32 v17, v17, v20
	v_add_f32_e32 v20, 1.0, v21
	v_rcp_f32_e32 v20, v20
	v_add_f32_e32 v21, 1.0, v22
	v_rcp_f32_e32 v21, v21
	v_pk_mul_f32 v[26:27], v[26:27], v[76:77] op_sel_hi:[1,0]
	v_mul_f32_e32 v18, v24, v18
	v_mul_f32_e32 v18, v18, v20
	v_mul_f32_e32 v19, v25, v19
	v_mul_f32_e32 v20, 0xbfb8aa3b, v26
	v_mul_f32_e32 v19, v19, v21
	v_exp_f32_e32 v20, v20
	v_mul_f32_e32 v21, 0xbfb8aa3b, v27
	v_exp_f32_e32 v21, v21
	v_cvt_pk_bf16_f32 v18, v18, v19
	v_add_f32_e32 v19, 1.0, v20
	v_rcp_f32_e32 v19, v19
	v_add_f32_e32 v20, 1.0, v21
	v_rcp_f32_e32 v20, v20
	v_mul_f32_e32 v21, v26, v32
	v_mul_f32_e32 v19, v21, v19
	v_mul_f32_e32 v21, v27, v33
	v_mul_f32_e32 v20, v21, v20
	v_cvt_pk_bf16_f32 v19, v19, v20
	v_mad_i64_i32 v[20:21], s[20:21], v66, s48, v[112:113]
	v_lshl_add_u64 v[20:21], v[20:21], 0, v[114:115]
	v_pk_mul_f32 v[12:13], v[12:13], v[68:69] op_sel_hi:[1,0]
	global_store_dwordx4 v[20:21], v[16:19], off
	v_pk_mul_f32 v[4:5], v[4:5], v[68:69] op_sel_hi:[1,0]
	v_pk_mul_f32 v[14:15], v[14:15], v[68:69] op_sel_hi:[1,0]
	v_pk_mul_f32 v[16:17], v[2:3], v[68:69] op_sel_hi:[1,0]
	v_mul_f32_e32 v2, 0xbfb8aa3b, v12
	v_exp_f32_e32 v18, v2
	v_mul_f32_e32 v2, 0xbfb8aa3b, v13
	v_exp_f32_e32 v19, v2
	v_pk_mul_f32 v[2:3], v[0:1], v[68:69] op_sel_hi:[1,0]
	v_add_f32_e32 v0, 1.0, v18
	v_rcp_f32_e32 v0, v0
	v_add_f32_e32 v1, 1.0, v19
	v_rcp_f32_e32 v1, v1
	v_mul_f32_e32 v4, v12, v4
	v_mul_f32_e32 v0, v4, v0
	v_mul_f32_e32 v4, v13, v5
	v_mul_f32_e32 v1, v4, v1
	v_mul_f32_e32 v4, 0xbfb8aa3b, v14
	v_exp_f32_e32 v4, v4
	v_mul_f32_e32 v5, 0xbfb8aa3b, v15
	v_exp_f32_e32 v5, v5
	v_cvt_pk_bf16_f32 v0, v0, v1
	v_add_f32_e32 v1, 1.0, v4
	v_rcp_f32_e32 v1, v1
	v_add_f32_e32 v4, 1.0, v5
	v_rcp_f32_e32 v4, v4
	v_pk_mul_f32 v[6:7], v[6:7], v[68:69] op_sel_hi:[1,0]
	v_pk_mul_f32 v[8:9], v[8:9], v[68:69] op_sel_hi:[1,0]
	v_mul_f32_e32 v5, v14, v6
	v_mul_f32_e32 v1, v5, v1
	v_mul_f32_e32 v5, v15, v7
	v_mul_f32_e32 v4, v5, v4
	v_mul_f32_e32 v5, 0xbfb8aa3b, v8
	v_exp_f32_e32 v5, v5
	v_mul_f32_e32 v6, 0xbfb8aa3b, v9
	v_exp_f32_e32 v6, v6
	v_cvt_pk_bf16_f32 v1, v1, v4
	v_add_f32_e32 v4, 1.0, v5
	v_rcp_f32_e32 v4, v4
	v_add_f32_e32 v5, 1.0, v6
	v_rcp_f32_e32 v5, v5
	v_pk_mul_f32 v[10:11], v[10:11], v[68:69] op_sel_hi:[1,0]
	v_mul_f32_e32 v2, v8, v2
	v_mul_f32_e32 v2, v2, v4
	v_mul_f32_e32 v3, v9, v3
	v_mul_f32_e32 v4, 0xbfb8aa3b, v10
	v_mul_f32_e32 v3, v3, v5
	v_exp_f32_e32 v4, v4
	v_mul_f32_e32 v5, 0xbfb8aa3b, v11
	v_exp_f32_e32 v5, v5
	v_cvt_pk_bf16_f32 v2, v2, v3
	v_add_f32_e32 v3, 1.0, v4
	v_rcp_f32_e32 v3, v3
	v_add_f32_e32 v4, 1.0, v5
	v_rcp_f32_e32 v4, v4
	v_mul_f32_e32 v5, v10, v16
	v_mul_f32_e32 v3, v5, v3
	v_mul_f32_e32 v5, v11, v17
	v_mul_f32_e32 v4, v5, v4
	v_cvt_pk_bf16_f32 v3, v3, v4
	v_mad_i64_i32 v[4:5], s[20:21], v64, s48, v[112:113]
	v_lshl_add_u64 v[4:5], v[4:5], 0, v[114:115]
	global_store_dwordx4 v[4:5], v[0:3], off
	s_cbranch_vccnz .LBB0_2119
	s_andn2_b64 vcc, exec, s[4:5]
	s_cbranch_vccnz .LBB0_2118
	s_barrier
	s_branch .LBB0_2118
